# P9 conv epilogue: bias folded into the first fma of 36 conv chains (one packed op less each)
# speedup vs baseline: 1.0027x; 1.0027x over previous
; __device__ __forceinline__ void st_bf4(bf16_t* p, f32x4 v) { u32x2 w; w.x = pk2(v[0], v[1]); w.y = pk2(v[2], v[3]); *(u32x2*)p = w; }
; __device__ __forceinline__ float sigmoidf_(float x) { return __builtin_amdgcn_rcpf(1.f + __expf(-x)); }
; __device__ __forceinline__ float dpp_ror1(float v) { return __int_as_float(__builtin_amdgcn_update_dpp(0, __float_as_int(v), 0x121, 0xf, 0xf, false)); }
; __device__ __forceinline__ float dpp_rol1(float v) { return __int_as_float(__builtin_amdgcn_update_dpp(0, __float_as_int(v), 0x12F, 0xf, 0xf, false)); }
;     __device__ __forceinline__ void tile(const f32x4 (&acc)[2][2][4][2], const Unit& u, int wr, int wc, int fr, int fq) const {
;     ...
;         for (int n = 0; n < 2; ++n) {
;             const int cv = 128 * u.pn + 32 * wc + 16 * n + 4 * fq, cg = FF + cv;
;             const f32x4 wv0 = *(const f32x4*)(cw + cv), wv1 = *(const f32x4*)(cw + F2 + cv), wv2 = *(const f32x4*)(cw + 2 * F2 + cv), bv = *(const f32x4*)(cb + cv);
;             const f32x4 wg0 = *(const f32x4*)(cw + cg), wg1 = *(const f32x4*)(cw + F2 + cg), wg2 = *(const f32x4*)(cw + 2 * F2 + cg), bg = *(const f32x4*)(cb + cg);
; #pragma unroll
;             for (int ai = 0; ai < 2; ++ai)
; #pragma unroll
;                 for (int m = 0; m < 4; ++m) {
;                     f32x4 r;
; #pragma unroll
;                     for (int i = 0; i < 4; ++i) {
;                         const float xv = acc[ai][0][m][n][i], xg = acc[ai][1][m][n][i];
;                         const float uv = m > 0 ? acc[ai][0][m > 0 ? m - 1 : 0][n][i] : 0.f, ug = m > 0 ? acc[ai][1][m > 0 ? m - 1 : 0][n][i] : 0.f;
;                         const float dv = m < 3 ? acc[ai][0][m < 3 ? m + 1 : 3][n][i] : 0.f, dg = m < 3 ? acc[ai][1][m < 3 ? m + 1 : 3][n][i] : 0.f;
;                         const float pv = dpp_ror1(fr == 15 ? uv : xv), pg = dpp_ror1(fr == 15 ? ug : xg);
;                         const float nv = dpp_rol1(fr == 0 ? dv : xv), ng = dpp_rol1(fr == 0 ? dg : xg);
;                         const float yv = wv0[i] * pv + wv1[i] * xv + wv2[i] * nv + bv[i];
;                         const float yg = wg0[i] * pg + wg1[i] * xg + wg2[i] * ng + bg[i];
;                         r[i] = yg * sigmoidf_(yg) * yv;
;                     }
;                     st_bf4(ACT + (size_t)(u.pm * BM + ai * HALF + wr * 64 + m * 16 + fr) * FF + cv, r);
;                 }
.LBB0_1802:
	v_lshl_or_b32 v170, s33, 7, v204
	v_ashrrev_i32_e32 v171, 31, v170
	v_lshlrev_b64 v[120:121], 2, v[170:171]
	v_lshl_add_u64 v[172:173], s[56:57], 0, v[120:121]
	v_add_co_u32_e32 v176, vcc, 0x5000, v172
	v_lshl_add_u64 v[122:123], s[12:13], 0, v[120:121]
	s_nop 0
	v_addc_co_u32_e32 v177, vcc, 0, v173, vcc
	v_add_co_u32_e32 v178, vcc, 0x5000, v122
	v_lshl_add_u64 v[124:125], s[14:15], 0, v[120:121]
	s_nop 0
	v_addc_co_u32_e32 v179, vcc, 0, v123, vcc
	global_load_dwordx4 v[132:135], v[176:177], off offset:2048
	global_load_dwordx4 v[148:151], v[178:179], off offset:2048
	v_add_co_u32_e32 v180, vcc, 0x5000, v124
	v_lshl_add_u64 v[174:175], s[58:59], 0, v[120:121]
	s_nop 0
	v_addc_co_u32_e32 v181, vcc, 0, v125, vcc
	global_load_dwordx4 v[136:139], v[180:181], off offset:2048
	v_add_co_u32_e32 v182, vcc, 0x5000, v174
	s_nop 0
	v_addc_co_u32_e32 v183, vcc, 0, v175, vcc
	global_load_dwordx4 v[140:143], v[182:183], off offset:2048
	global_load_dwordx4 v[230:233], v[176:177], off offset:2112
	global_load_dwordx4 v[234:237], v[178:179], off offset:2112
	global_load_dwordx4 v[238:241], v[180:181], off offset:2112
	global_load_dwordx4 v[242:245], v[182:183], off offset:2112
	global_load_dwordx4 v[246:249], v[122:123], off offset:64
	global_load_dwordx4 v[144:147], v[122:123], off
	s_nop 0
	global_load_dwordx4 v[250:253], v[172:173], off offset:64
	global_load_dwordx4 v[120:123], v[172:173], off
	s_nop 0
	global_load_dwordx4 v[190:193], v[124:125], off offset:64
	global_load_dwordx4 v[124:127], v[124:125], off
	s_nop 0
	global_load_dwordx4 v[128:131], v[174:175], off
	s_nop 0
	global_load_dwordx4 v[180:183], v[174:175], off offset:64
	v_mov_b32_dpp v208, v156 row_shr:1 row_mask:0xf bank_mask:0xf bound_ctrl:1
	v_mov_b32_dpp v168, v152 row_shr:1 row_mask:0xf bank_mask:0xf bound_ctrl:1
	v_cndmask_b32_e64 v169, v156, v116, s[6:7]
	s_nop 1
	v_mov_b32_dpp v210, v169 row_ror:15 row_mask:0xf bank_mask:0xf
	v_cndmask_b32_e64 v169, v152, v112, s[6:7]
	s_nop 1
	v_mov_b32_dpp v186, v169 row_ror:15 row_mask:0xf bank_mask:0xf
	v_mov_b32_dpp v209, v157 row_shr:1 row_mask:0xf bank_mask:0xf bound_ctrl:1
	v_mov_b32_dpp v169, v153 row_shr:1 row_mask:0xf bank_mask:0xf bound_ctrl:1
	v_cndmask_b32_e64 v184, v157, v117, s[6:7]
	s_nop 1
	v_mov_b32_dpp v211, v184 row_ror:15 row_mask:0xf bank_mask:0xf
	v_cndmask_b32_e64 v184, v153, v113, s[6:7]
	s_lshl_b32 s17, s26, 8
	s_nop 0
	v_mov_b32_dpp v187, v184 row_ror:15 row_mask:0xf bank_mask:0xf
	v_add_u32_e32 v220, s17, v195
	s_andn2_b64 vcc, exec, s[20:21]
	v_mov_b32_dpp v212, v158 row_shr:1 row_mask:0xf bank_mask:0xf bound_ctrl:1
	s_mov_b64 s[20:21], -1
	s_waitcnt vmcnt(0)
	v_pk_mul_f32 v[222:223], v[152:153], v[148:149]
	s_nop 0
	v_pk_fma_f32 v[168:169], v[132:133], v[168:169], v[222:223]
	v_mov_b32_dpp v214, v154 row_shr:1 row_mask:0xf bank_mask:0xf bound_ctrl:1
	v_cndmask_b32_e64 v184, v158, v118, s[6:7]
	v_pk_fma_f32 v[168:169], v[136:137], v[186:187], v[168:169]
	v_lshlrev_b64 v[186:187], 1, v[170:171]
	v_pk_add_f32 v[222:223], v[140:141], v[168:169]
	v_mov_b32_dpp v216, v184 row_ror:15 row_mask:0xf bank_mask:0xf
	v_mul_f32_e32 v168, 0xbfb8aa3b, v222
	v_exp_f32_e32 v224, v168
	v_cndmask_b32_e64 v184, v154, v114, s[6:7]
	v_pk_fma_f32 v[228:229], v[156:157], v[144:145], v[128:129]
	v_pk_fma_f32 v[226:227], v[158:159], v[146:147], v[130:131]
	v_add_f32_e32 v171, 1.0, v224
	v_mul_f32_e32 v224, 0xbfb8aa3b, v223
	v_exp_f32_e32 v225, v224
	v_mov_b32_dpp v218, v184 row_ror:15 row_mask:0xf bank_mask:0xf
	v_rcp_f32_e32 v224, v171
	v_add_f32_e32 v171, 1.0, v225
	v_mov_b32_dpp v213, v159 row_shr:1 row_mask:0xf bank_mask:0xf bound_ctrl:1
	v_rcp_f32_e32 v225, v171
	v_pk_fma_f32 v[208:209], v[120:121], v[208:209], v[228:229]
	v_mov_b32_dpp v215, v155 row_shr:1 row_mask:0xf bank_mask:0xf bound_ctrl:1
	v_cndmask_b32_e64 v184, v159, v119, s[6:7]
	v_pk_fma_f32 v[208:209], v[124:125], v[210:211], v[208:209]
	v_pk_mul_f32 v[210:211], v[222:223], v[224:225]
	v_mov_b32_dpp v217, v184 row_ror:15 row_mask:0xf bank_mask:0xf
	v_cndmask_b32_e64 v184, v155, v115, s[6:7]
	v_pk_fma_f32 v[212:213], v[122:123], v[212:213], v[226:227]
	s_nop 0
	v_mov_b32_dpp v219, v184 row_ror:15 row_mask:0xf bank_mask:0xf
	v_mov_b64_e32 v[184:185], s[0:1]
	v_mad_i64_i32 v[220:221], s[28:29], v220, s46, v[184:185]
	v_lshl_add_u64 v[168:169], v[220:221], 0, v[186:187]
	v_pk_fma_f32 v[220:221], v[154:155], v[150:151], v[142:143]
	v_pk_mul_f32 v[208:209], v[208:209], v[210:211]
	v_pk_fma_f32 v[210:211], v[134:135], v[214:215], v[220:221]
	v_pk_fma_f32 v[212:213], v[126:127], v[216:217], v[212:213]
	v_pk_fma_f32 v[210:211], v[138:139], v[218:219], v[210:211]
	v_cvt_pk_bf16_f32 v208, v208, v209
	v_mul_f32_e32 v171, 0xbfb8aa3b, v210
	v_exp_f32_e32 v171, v171
	v_mul_f32_e32 v214, 0xbfb8aa3b, v211
	v_exp_f32_e32 v215, v214
	v_pk_mul_f32 v[216:217], v[112:113], v[148:149]
	v_add_f32_e32 v171, 1.0, v171
	v_rcp_f32_e32 v214, v171
	v_add_f32_e32 v171, 1.0, v215
	v_rcp_f32_e32 v215, v171
	v_cndmask_b32_e64 v171, v116, v156, s[4:5]
	v_pk_fma_f32 v[222:223], v[116:117], v[144:145], v[128:129]
	v_pk_mul_f32 v[210:211], v[210:211], v[214:215]
	v_mov_b32_dpp v156, v171 row_ror:1 row_mask:0xf bank_mask:0xf
	v_pk_mul_f32 v[210:211], v[212:213], v[210:211]
	v_cndmask_b32_e64 v171, v112, v152, s[4:5]
	v_cvt_pk_bf16_f32 v209, v210, v211
	global_store_dwordx2 v[168:169], v[208:209], off
	v_mov_b32_dpp v152, v171 row_ror:1 row_mask:0xf bank_mask:0xf
	v_cndmask_b32_e64 v171, v116, v108, s[6:7]
	s_nop 1
	v_mov_b32_dpp v208, v171 row_ror:15 row_mask:0xf bank_mask:0xf
	v_cndmask_b32_e64 v171, v112, v104, s[6:7]
	s_nop 1
	v_mov_b32_dpp v210, v171 row_ror:15 row_mask:0xf bank_mask:0xf
; __device__ __forceinline__ void st_bf4(bf16_t* p, f32x4 v) { u32x2 w; w.x = pk2(v[0], v[1]); w.y = pk2(v[2], v[3]); *(u32x2*)p = w; }
; __device__ __forceinline__ float sigmoidf_(float x) { return __builtin_amdgcn_rcpf(1.f + __expf(-x)); }
; __device__ __forceinline__ float dpp_ror1(float v) { return __int_as_float(__builtin_amdgcn_update_dpp(0, __float_as_int(v), 0x121, 0xf, 0xf, false)); }
; __device__ __forceinline__ float dpp_rol1(float v) { return __int_as_float(__builtin_amdgcn_update_dpp(0, __float_as_int(v), 0x12F, 0xf, 0xf, false)); }
;     __device__ __forceinline__ void tile(const f32x4 (&acc)[2][2][4][2], const Unit& u, int wr, int wc, int fr, int fq) const {
;     ...
;         for (int n = 0; n < 2; ++n) {
;             const int cv = 128 * u.pn + 32 * wc + 16 * n + 4 * fq, cg = FF + cv;
;             const f32x4 wv0 = *(const f32x4*)(cw + cv), wv1 = *(const f32x4*)(cw + F2 + cv), wv2 = *(const f32x4*)(cw + 2 * F2 + cv), bv = *(const f32x4*)(cb + cv);
;             const f32x4 wg0 = *(const f32x4*)(cw + cg), wg1 = *(const f32x4*)(cw + F2 + cg), wg2 = *(const f32x4*)(cw + 2 * F2 + cg), bg = *(const f32x4*)(cb + cg);
; #pragma unroll
;             for (int ai = 0; ai < 2; ++ai)
; #pragma unroll
;                 for (int m = 0; m < 4; ++m) {
;                     f32x4 r;
; #pragma unroll
;                     for (int i = 0; i < 4; ++i) {
;                         const float xv = acc[ai][0][m][n][i], xg = acc[ai][1][m][n][i];
;                         const float uv = m > 0 ? acc[ai][0][m > 0 ? m - 1 : 0][n][i] : 0.f, ug = m > 0 ? acc[ai][1][m > 0 ? m - 1 : 0][n][i] : 0.f;
;                         const float dv = m < 3 ? acc[ai][0][m < 3 ? m + 1 : 3][n][i] : 0.f, dg = m < 3 ? acc[ai][1][m < 3 ? m + 1 : 3][n][i] : 0.f;
;                         const float pv = dpp_ror1(fr == 15 ? uv : xv), pg = dpp_ror1(fr == 15 ? ug : xg);
;                         const float nv = dpp_rol1(fr == 0 ? dv : xv), ng = dpp_rol1(fr == 0 ? dg : xg);
;                         const float yv = wv0[i] * pv + wv1[i] * xv + wv2[i] * nv + bv[i];
;                         const float yg = wg0[i] * pg + wg1[i] * xg + wg2[i] * ng + bg[i];
;                         r[i] = yg * sigmoidf_(yg) * yv;
;                     }
;                     st_bf4(ACT + (size_t)(u.pm * BM + ai * HALF + wr * 64 + m * 16 + fr) * FF + cv, r);
;                 }
	v_cndmask_b32_e64 v171, v117, v157, s[4:5]
	s_nop 1
	v_mov_b32_dpp v157, v171 row_ror:1 row_mask:0xf bank_mask:0xf
	v_cndmask_b32_e64 v171, v113, v153, s[4:5]
	v_pk_fma_f32 v[156:157], v[120:121], v[156:157], v[222:223]
	s_nop 0
	v_mov_b32_dpp v153, v171 row_ror:1 row_mask:0xf bank_mask:0xf
	v_cndmask_b32_e64 v171, v117, v109, s[6:7]
	v_pk_fma_f32 v[152:153], v[132:133], v[152:153], v[216:217]
	v_pk_mul_f32 v[216:217], v[114:115], v[150:151]
	v_mov_b32_dpp v209, v171 row_ror:15 row_mask:0xf bank_mask:0xf
	v_cndmask_b32_e64 v171, v113, v105, s[6:7]
	v_pk_fma_f32 v[156:157], v[124:125], v[208:209], v[156:157]
	v_pk_fma_f32 v[220:221], v[118:119], v[146:147], v[130:131]
	v_mov_b32_dpp v211, v171 row_ror:15 row_mask:0xf bank_mask:0xf
	v_cndmask_b32_e64 v171, v118, v158, s[4:5]
	v_pk_fma_f32 v[152:153], v[136:137], v[210:211], v[152:153]
	s_nop 0
	v_mov_b32_dpp v158, v171 row_ror:1 row_mask:0xf bank_mask:0xf
	v_cndmask_b32_e64 v171, v114, v154, s[4:5]
	v_pk_add_f32 v[210:211], v[140:141], v[152:153]
	s_nop 0
	v_mov_b32_dpp v154, v171 row_ror:1 row_mask:0xf bank_mask:0xf
	v_cndmask_b32_e64 v171, v118, v110, s[6:7]
	v_mul_f32_e32 v152, 0xbfb8aa3b, v210
	v_exp_f32_e32 v218, v152
	v_mov_b32_dpp v212, v171 row_ror:15 row_mask:0xf bank_mask:0xf
	v_cndmask_b32_e64 v171, v114, v106, s[6:7]
	s_nop 1
	v_mov_b32_dpp v214, v171 row_ror:15 row_mask:0xf bank_mask:0xf
	v_cndmask_b32_e64 v171, v119, v159, s[4:5]
	s_nop 1
	v_mov_b32_dpp v159, v171 row_ror:1 row_mask:0xf bank_mask:0xf
	v_cndmask_b32_e64 v171, v115, v155, s[4:5]
	v_pk_fma_f32 v[158:159], v[122:123], v[158:159], v[220:221]
	s_nop 0
	v_mov_b32_dpp v155, v171 row_ror:1 row_mask:0xf bank_mask:0xf
	v_cndmask_b32_e64 v171, v119, v111, s[6:7]
	v_pk_fma_f32 v[154:155], v[134:135], v[154:155], v[216:217]
	v_pk_fma_f32 v[216:217], v[108:109], v[144:145], v[128:129]
	v_mov_b32_dpp v213, v171 row_ror:15 row_mask:0xf bank_mask:0xf
	v_cndmask_b32_e64 v171, v115, v107, s[6:7]
	v_pk_fma_f32 v[158:159], v[126:127], v[212:213], v[158:159]
	s_nop 0
	v_mov_b32_dpp v215, v171 row_ror:15 row_mask:0xf bank_mask:0xf
	v_add_u32_e32 v171, s17, v197
	v_mad_i64_i32 v[152:153], s[28:29], v171, s46, v[184:185]
	v_add_f32_e32 v171, 1.0, v218
	v_mul_f32_e32 v218, 0xbfb8aa3b, v211
	v_exp_f32_e32 v219, v218
	v_rcp_f32_e32 v218, v171
	v_pk_fma_f32 v[154:155], v[138:139], v[214:215], v[154:155]
	v_add_f32_e32 v171, 1.0, v219
	v_rcp_f32_e32 v219, v171
	v_pk_add_f32 v[154:155], v[142:143], v[154:155]
	v_lshl_add_u64 v[152:153], v[152:153], 0, v[186:187]
	v_mul_f32_e32 v171, 0xbfb8aa3b, v154
	v_pk_mul_f32 v[208:209], v[210:211], v[218:219]
	v_exp_f32_e32 v171, v171
	v_pk_mul_f32 v[156:157], v[156:157], v[208:209]
	v_mul_f32_e32 v208, 0xbfb8aa3b, v155
	v_exp_f32_e32 v209, v208
	v_cvt_pk_bf16_f32 v156, v156, v157
	v_add_f32_e32 v157, 1.0, v171
	v_rcp_f32_e32 v208, v157
	v_add_f32_e32 v157, 1.0, v209
	v_rcp_f32_e32 v209, v157
	v_pk_mul_f32 v[210:211], v[104:105], v[148:149]
	v_cndmask_b32_e64 v171, v111, v103, s[6:7]
	v_pk_fma_f32 v[214:215], v[110:111], v[146:147], v[130:131]
	v_pk_mul_f32 v[154:155], v[154:155], v[208:209]
	s_nop 0
	v_pk_mul_f32 v[154:155], v[158:159], v[154:155]
	v_cndmask_b32_e64 v158, v105, v97, s[6:7]
	v_cvt_pk_bf16_f32 v157, v154, v155
	v_cndmask_b32_e64 v154, v108, v116, s[4:5]
	v_cndmask_b32_e64 v155, v108, v100, s[6:7]
	global_store_dwordx2 v[152:153], v[156:157], off
	v_mov_b32_dpp v116, v154 row_ror:1 row_mask:0xf bank_mask:0xf
	v_cndmask_b32_e64 v154, v104, v112, s[4:5]
	v_cndmask_b32_e64 v157, v109, v101, s[6:7]
	s_nop 0
	v_mov_b32_dpp v112, v154 row_ror:1 row_mask:0xf bank_mask:0xf
	v_cndmask_b32_e64 v159, v110, v102, s[6:7]
	v_mov_b32_dpp v154, v155 row_ror:15 row_mask:0xf bank_mask:0xf
	v_cndmask_b32_e64 v155, v104, v96, s[6:7]
	s_nop 1
	v_mov_b32_dpp v156, v155 row_ror:15 row_mask:0xf bank_mask:0xf
	v_cndmask_b32_e64 v155, v109, v117, s[4:5]
	s_nop 1
	v_mov_b32_dpp v117, v155 row_ror:1 row_mask:0xf bank_mask:0xf
	v_cndmask_b32_e64 v155, v105, v113, s[4:5]
	v_pk_fma_f32 v[116:117], v[120:121], v[116:117], v[216:217]
	s_nop 0
	v_mov_b32_dpp v113, v155 row_ror:1 row_mask:0xf bank_mask:0xf
	v_pk_fma_f32 v[112:113], v[132:133], v[112:113], v[210:211]
	v_pk_fma_f32 v[210:211], v[106:107], v[150:151], v[142:143]
	v_mov_b32_dpp v155, v157 row_ror:15 row_mask:0xf bank_mask:0xf
	v_pk_fma_f32 v[116:117], v[124:125], v[154:155], v[116:117]
	s_nop 0
	v_mov_b32_dpp v157, v158 row_ror:15 row_mask:0xf bank_mask:0xf
	v_cndmask_b32_e64 v158, v110, v118, s[4:5]
	v_pk_fma_f32 v[112:113], v[136:137], v[156:157], v[112:113]
	s_nop 0
	v_mov_b32_dpp v118, v158 row_ror:1 row_mask:0xf bank_mask:0xf
	v_cndmask_b32_e64 v158, v106, v114, s[4:5]
	v_pk_add_f32 v[156:157], v[140:141], v[112:113]
	s_nop 0
	v_mov_b32_dpp v114, v158 row_ror:1 row_mask:0xf bank_mask:0xf
	v_mul_f32_e32 v112, 0xbfb8aa3b, v156
	v_exp_f32_e32 v212, v112
	v_mov_b32_dpp v158, v159 row_ror:15 row_mask:0xf bank_mask:0xf
	v_cndmask_b32_e64 v159, v106, v98, s[6:7]
	s_nop 1
	v_mov_b32_dpp v208, v159 row_ror:15 row_mask:0xf bank_mask:0xf
	v_cndmask_b32_e64 v159, v111, v119, s[4:5]
	s_nop 1
	v_mov_b32_dpp v119, v159 row_ror:1 row_mask:0xf bank_mask:0xf
	v_cndmask_b32_e64 v159, v107, v115, s[4:5]
	v_pk_fma_f32 v[118:119], v[122:123], v[118:119], v[214:215]
	s_nop 0
	v_mov_b32_dpp v115, v159 row_ror:1 row_mask:0xf bank_mask:0xf
	v_pk_fma_f32 v[114:115], v[134:135], v[114:115], v[210:211]
	s_nop 0
	v_mov_b32_dpp v159, v171 row_ror:15 row_mask:0xf bank_mask:0xf
	v_cndmask_b32_e64 v171, v107, v99, s[6:7]
	v_pk_fma_f32 v[118:119], v[126:127], v[158:159], v[118:119]
	s_nop 0
	v_mov_b32_dpp v209, v171 row_ror:15 row_mask:0xf bank_mask:0xf
	v_add_u32_e32 v171, s17, v198
; __device__ __forceinline__ void st_bf4(bf16_t* p, f32x4 v) { u32x2 w; w.x = pk2(v[0], v[1]); w.y = pk2(v[2], v[3]); *(u32x2*)p = w; }
; __device__ __forceinline__ float sigmoidf_(float x) { return __builtin_amdgcn_rcpf(1.f + __expf(-x)); }
; __device__ __forceinline__ float dpp_ror1(float v) { return __int_as_float(__builtin_amdgcn_update_dpp(0, __float_as_int(v), 0x121, 0xf, 0xf, false)); }
; __device__ __forceinline__ float dpp_rol1(float v) { return __int_as_float(__builtin_amdgcn_update_dpp(0, __float_as_int(v), 0x12F, 0xf, 0xf, false)); }
;     __device__ __forceinline__ void tile(const f32x4 (&acc)[2][2][4][2], const Unit& u, int wr, int wc, int fr, int fq) const {
;     ...
;         for (int n = 0; n < 2; ++n) {
;             const int cv = 128 * u.pn + 32 * wc + 16 * n + 4 * fq, cg = FF + cv;
;             const f32x4 wv0 = *(const f32x4*)(cw + cv), wv1 = *(const f32x4*)(cw + F2 + cv), wv2 = *(const f32x4*)(cw + 2 * F2 + cv), bv = *(const f32x4*)(cb + cv);
;             const f32x4 wg0 = *(const f32x4*)(cw + cg), wg1 = *(const f32x4*)(cw + F2 + cg), wg2 = *(const f32x4*)(cw + 2 * F2 + cg), bg = *(const f32x4*)(cb + cg);
; #pragma unroll
;             for (int ai = 0; ai < 2; ++ai)
; #pragma unroll
;                 for (int m = 0; m < 4; ++m) {
;                     f32x4 r;
; #pragma unroll
;                     for (int i = 0; i < 4; ++i) {
;                         const float xv = acc[ai][0][m][n][i], xg = acc[ai][1][m][n][i];
;                         const float uv = m > 0 ? acc[ai][0][m > 0 ? m - 1 : 0][n][i] : 0.f, ug = m > 0 ? acc[ai][1][m > 0 ? m - 1 : 0][n][i] : 0.f;
;                         const float dv = m < 3 ? acc[ai][0][m < 3 ? m + 1 : 3][n][i] : 0.f, dg = m < 3 ? acc[ai][1][m < 3 ? m + 1 : 3][n][i] : 0.f;
;                         const float pv = dpp_ror1(fr == 15 ? uv : xv), pg = dpp_ror1(fr == 15 ? ug : xg);
;                         const float nv = dpp_rol1(fr == 0 ? dv : xv), ng = dpp_rol1(fr == 0 ? dg : xg);
;                         const float yv = wv0[i] * pv + wv1[i] * xv + wv2[i] * nv + bv[i];
;                         const float yg = wg0[i] * pg + wg1[i] * xg + wg2[i] * ng + bg[i];
;                         r[i] = yg * sigmoidf_(yg) * yv;
;                     }
;                     st_bf4(ACT + (size_t)(u.pm * BM + ai * HALF + wr * 64 + m * 16 + fr) * FF + cv, r);
;                 }
	v_mad_i64_i32 v[112:113], s[28:29], v171, s46, v[184:185]
	v_add_f32_e32 v171, 1.0, v212
	v_mul_f32_e32 v212, 0xbfb8aa3b, v157
	v_exp_f32_e32 v213, v212
	v_rcp_f32_e32 v212, v171
	v_pk_fma_f32 v[114:115], v[138:139], v[208:209], v[114:115]
	v_add_f32_e32 v171, 1.0, v213
	v_rcp_f32_e32 v213, v171
	v_lshl_add_u64 v[112:113], v[112:113], 0, v[186:187]
	v_pk_mul_f32 v[154:155], v[156:157], v[212:213]
	s_nop 0
	v_pk_mul_f32 v[116:117], v[116:117], v[154:155]
	v_mul_f32_e32 v154, 0xbfb8aa3b, v114
	v_exp_f32_e32 v154, v154
	v_mul_f32_e32 v155, 0xbfb8aa3b, v115
	v_exp_f32_e32 v155, v155
	v_cvt_pk_bf16_f32 v116, v116, v117
	v_add_f32_e32 v117, 1.0, v154
	v_rcp_f32_e32 v154, v117
	v_add_f32_e32 v117, 1.0, v155
	v_rcp_f32_e32 v155, v117
	v_cndmask_b32_e64 v156, v99, 0, s[6:7]
	v_pk_mul_f32 v[114:115], v[114:115], v[154:155]
	s_nop 0
	v_pk_mul_f32 v[114:115], v[118:119], v[114:115]
	v_cndmask_b32_e64 v118, v97, 0, s[6:7]
	v_cvt_pk_bf16_f32 v117, v114, v115
	v_cndmask_b32_e64 v114, v100, v108, s[4:5]
	global_store_dwordx2 v[112:113], v[116:117], off
	s_nop 0
	v_mov_b32_dpp v108, v114 row_ror:1 row_mask:0xf bank_mask:0xf
	v_cndmask_b32_e64 v114, v96, v104, s[4:5]
	v_cndmask_b32_e64 v117, v101, 0, s[6:7]
	s_nop 0
	v_mov_b32_dpp v104, v114 row_ror:1 row_mask:0xf bank_mask:0xf
	v_mov_b32_dpp v114, v100 row_shl:1 row_mask:0xf bank_mask:0xf bound_ctrl:1
	s_nop 0
	v_mov_b32_dpp v116, v96 row_shl:1 row_mask:0xf bank_mask:0xf bound_ctrl:1
	v_cndmask_b32_e64 v115, v101, v109, s[4:5]
	v_pk_mul_f32 v[100:101], v[100:101], v[144:145]
	s_nop 0
	v_mov_b32_dpp v109, v115 row_ror:1 row_mask:0xf bank_mask:0xf
	v_cndmask_b32_e64 v115, v97, v105, s[4:5]
	v_pk_mul_f32 v[96:97], v[96:97], v[148:149]
	v_pk_fma_f32 v[100:101], v[120:121], v[108:109], v[100:101]
	v_mov_b32_dpp v105, v115 row_ror:1 row_mask:0xf bank_mask:0xf
	v_pk_fma_f32 v[96:97], v[132:133], v[104:105], v[96:97]
	v_mov_b32_dpp v115, v117 row_ror:15 row_mask:0xf bank_mask:0xf
	v_pk_fma_f32 v[100:101], v[124:125], v[114:115], v[100:101]
	v_mov_b32_dpp v117, v118 row_ror:15 row_mask:0xf bank_mask:0xf
	v_pk_fma_f32 v[96:97], v[136:137], v[116:117], v[96:97]
	v_cndmask_b32_e64 v118, v102, v110, s[4:5]
	v_pk_add_f32 v[104:105], v[140:141], v[96:97]
	s_nop 0
	v_mul_f32_e32 v96, 0xbfb8aa3b, v104
	v_mul_f32_e32 v117, 0xbfb8aa3b, v105
	v_mov_b32_dpp v110, v118 row_ror:1 row_mask:0xf bank_mask:0xf
	v_cndmask_b32_e64 v118, v98, v106, s[4:5]
	v_exp_f32_e32 v116, v96
	v_exp_f32_e32 v117, v117
	v_mov_b32_dpp v106, v118 row_ror:1 row_mask:0xf bank_mask:0xf
	v_add_f32_e32 v116, 1.0, v116
	v_add_f32_e32 v117, 1.0, v117
	v_mov_b32_dpp v118, v102 row_shl:1 row_mask:0xf bank_mask:0xf bound_ctrl:1
	v_rcp_f32_e32 v116, v116
	v_rcp_f32_e32 v117, v117
	v_mov_b32_dpp v154, v98 row_shl:1 row_mask:0xf bank_mask:0xf bound_ctrl:1
	v_cndmask_b32_e64 v119, v103, v111, s[4:5]
	v_pk_add_f32 v[100:101], v[128:129], v[100:101]
	v_pk_mul_f32 v[104:105], v[104:105], v[116:117]
	v_mov_b32_dpp v111, v119 row_ror:1 row_mask:0xf bank_mask:0xf
	v_cndmask_b32_e64 v119, v99, v107, s[4:5]
	v_pk_mul_f32 v[98:99], v[98:99], v[150:151]
	v_pk_mul_f32 v[100:101], v[100:101], v[104:105]
	v_mov_b32_dpp v107, v119 row_ror:1 row_mask:0xf bank_mask:0xf
	v_pk_fma_f32 v[98:99], v[134:135], v[106:107], v[98:99]
	v_cvt_pk_bf16_f32 v100, v100, v101
	v_mov_b32_dpp v119, v103 row_shl:1 row_mask:0xf bank_mask:0xf bound_ctrl:1
	v_pk_mul_f32 v[102:103], v[102:103], v[146:147]
	v_cndmask_b32_e64 v106, v89, v81, s[6:7]
	v_mov_b32_dpp v155, v156 row_ror:15 row_mask:0xf bank_mask:0xf
	v_pk_fma_f32 v[98:99], v[138:139], v[154:155], v[98:99]
	v_pk_fma_f32 v[102:103], v[122:123], v[110:111], v[102:103]
	v_pk_add_f32 v[98:99], v[142:143], v[98:99]
	v_pk_fma_f32 v[102:103], v[126:127], v[118:119], v[102:103]
	v_mul_f32_e32 v104, 0xbfb8aa3b, v98
	v_exp_f32_e32 v104, v104
	v_mul_f32_e32 v105, 0xbfb8aa3b, v99
	v_exp_f32_e32 v105, v105
	v_add_u32_e32 v156, s17, v199
	v_add_f32_e32 v101, 1.0, v104
	v_rcp_f32_e32 v104, v101
	v_add_f32_e32 v101, 1.0, v105
	v_rcp_f32_e32 v105, v101
	v_pk_add_f32 v[102:103], v[130:131], v[102:103]
	v_mad_i64_i32 v[96:97], s[28:29], v156, s46, v[184:185]
	v_pk_mul_f32 v[98:99], v[98:99], v[104:105]
	v_lshl_add_u64 v[96:97], v[96:97], 0, v[186:187]
	v_pk_mul_f32 v[98:99], v[102:103], v[98:99]
	s_nop 0
	v_cvt_pk_bf16_f32 v101, v98, v99
	global_store_dwordx2 v[96:97], v[100:101], off
	v_mov_b32_dpp v100, v92 row_shr:1 row_mask:0xf bank_mask:0xf bound_ctrl:1
	v_mov_b32_dpp v98, v88 row_shr:1 row_mask:0xf bank_mask:0xf bound_ctrl:1
	v_cndmask_b32_e64 v99, v92, v84, s[6:7]
	v_cndmask_b32_e64 v105, v93, v85, s[6:7]
	s_nop 0
	v_mov_b32_dpp v102, v99 row_ror:15 row_mask:0xf bank_mask:0xf
	v_cndmask_b32_e64 v99, v88, v80, s[6:7]
	s_nop 1
	v_mov_b32_dpp v104, v99 row_ror:15 row_mask:0xf bank_mask:0xf
	v_cndmask_b32_e64 v115, v95, v87, s[6:7]
	v_mov_b32_dpp v101, v93 row_shr:1 row_mask:0xf bank_mask:0xf bound_ctrl:1
	v_cndmask_b32_e64 v116, v91, v83, s[6:7]
	v_add_u32_e32 v118, s17, v200
	v_mov_b32_dpp v99, v89 row_shr:1 row_mask:0xf bank_mask:0xf bound_ctrl:1
	v_pk_fma_f32 v[156:157], v[92:93], v[144:145], v[128:129]
	v_pk_fma_f32 v[154:155], v[94:95], v[146:147], v[130:131]
	v_mov_b32_dpp v103, v105 row_ror:15 row_mask:0xf bank_mask:0xf
	v_pk_fma_f32 v[100:101], v[120:121], v[100:101], v[156:157]
	s_nop 0
	v_mov_b32_dpp v105, v106 row_ror:15 row_mask:0xf bank_mask:0xf
	v_pk_fma_f32 v[100:101], v[124:125], v[102:103], v[100:101]
	s_nop 0
	v_mov_b32_dpp v106, v94 row_shr:1 row_mask:0xf bank_mask:0xf bound_ctrl:1
	s_nop 0
	v_mov_b32_dpp v108, v90 row_shr:1 row_mask:0xf bank_mask:0xf bound_ctrl:1
	v_cndmask_b32_e64 v107, v94, v86, s[6:7]
	s_nop 1
; __device__ __forceinline__ void st_bf4(bf16_t* p, f32x4 v) { u32x2 w; w.x = pk2(v[0], v[1]); w.y = pk2(v[2], v[3]); *(u32x2*)p = w; }
; __device__ __forceinline__ float sigmoidf_(float x) { return __builtin_amdgcn_rcpf(1.f + __expf(-x)); }
; __device__ __forceinline__ float dpp_ror1(float v) { return __int_as_float(__builtin_amdgcn_update_dpp(0, __float_as_int(v), 0x121, 0xf, 0xf, false)); }
; __device__ __forceinline__ float dpp_rol1(float v) { return __int_as_float(__builtin_amdgcn_update_dpp(0, __float_as_int(v), 0x12F, 0xf, 0xf, false)); }
;     __device__ __forceinline__ void tile(const f32x4 (&acc)[2][2][4][2], const Unit& u, int wr, int wc, int fr, int fq) const {
;     ...
;         for (int n = 0; n < 2; ++n) {
;             const int cv = 128 * u.pn + 32 * wc + 16 * n + 4 * fq, cg = FF + cv;
;             const f32x4 wv0 = *(const f32x4*)(cw + cv), wv1 = *(const f32x4*)(cw + F2 + cv), wv2 = *(const f32x4*)(cw + 2 * F2 + cv), bv = *(const f32x4*)(cb + cv);
;             const f32x4 wg0 = *(const f32x4*)(cw + cg), wg1 = *(const f32x4*)(cw + F2 + cg), wg2 = *(const f32x4*)(cw + 2 * F2 + cg), bg = *(const f32x4*)(cb + cg);
; #pragma unroll
;             for (int ai = 0; ai < 2; ++ai)
; #pragma unroll
;                 for (int m = 0; m < 4; ++m) {
;                     f32x4 r;
; #pragma unroll
;                     for (int i = 0; i < 4; ++i) {
;                         const float xv = acc[ai][0][m][n][i], xg = acc[ai][1][m][n][i];
;                         const float uv = m > 0 ? acc[ai][0][m > 0 ? m - 1 : 0][n][i] : 0.f, ug = m > 0 ? acc[ai][1][m > 0 ? m - 1 : 0][n][i] : 0.f;
;                         const float dv = m < 3 ? acc[ai][0][m < 3 ? m + 1 : 3][n][i] : 0.f, dg = m < 3 ? acc[ai][1][m < 3 ? m + 1 : 3][n][i] : 0.f;
;                         const float pv = dpp_ror1(fr == 15 ? uv : xv), pg = dpp_ror1(fr == 15 ? ug : xg);
;                         const float nv = dpp_rol1(fr == 0 ? dv : xv), ng = dpp_rol1(fr == 0 ? dg : xg);
;                         const float yv = wv0[i] * pv + wv1[i] * xv + wv2[i] * nv + bv[i];
;                         const float yg = wg0[i] * pg + wg1[i] * xg + wg2[i] * ng + bg[i];
;                         r[i] = yg * sigmoidf_(yg) * yv;
;                     }
;                     st_bf4(ACT + (size_t)(u.pm * BM + ai * HALF + wr * 64 + m * 16 + fr) * FF + cv, r);
;                 }
	v_mov_b32_dpp v110, v107 row_ror:15 row_mask:0xf bank_mask:0xf
	v_cndmask_b32_e64 v107, v90, v82, s[6:7]
	s_nop 1
	v_mov_b32_dpp v114, v107 row_ror:15 row_mask:0xf bank_mask:0xf
	s_nop 1
	v_mov_b32_dpp v107, v95 row_shr:1 row_mask:0xf bank_mask:0xf bound_ctrl:1
	v_pk_fma_f32 v[106:107], v[122:123], v[106:107], v[154:155]
	s_nop 0
	v_mov_b32_dpp v109, v91 row_shr:1 row_mask:0xf bank_mask:0xf bound_ctrl:1
	s_nop 1
	v_mov_b32_dpp v111, v115 row_ror:15 row_mask:0xf bank_mask:0xf
	v_pk_fma_f32 v[106:107], v[126:127], v[110:111], v[106:107]
	v_add_u32_e32 v110, s17, v201
	v_mov_b32_dpp v115, v116 row_ror:15 row_mask:0xf bank_mask:0xf
	v_pk_mul_f32 v[116:117], v[88:89], v[148:149]
	s_nop 0
	v_pk_fma_f32 v[98:99], v[132:133], v[98:99], v[116:117]
	v_pk_fma_f32 v[116:117], v[90:91], v[150:151], v[142:143]
	v_pk_fma_f32 v[98:99], v[136:137], v[104:105], v[98:99]
	s_nop 0
	v_pk_add_f32 v[104:105], v[140:141], v[98:99]
	s_nop 0
	v_mul_f32_e32 v98, 0xbfb8aa3b, v104
	v_exp_f32_e32 v119, v98
	v_mad_i64_i32 v[98:99], s[28:29], v118, s46, v[184:185]
	v_lshl_add_u64 v[98:99], v[98:99], 0, v[186:187]
	v_add_f32_e32 v118, 1.0, v119
	v_mul_f32_e32 v119, 0xbfb8aa3b, v105
	v_exp_f32_e32 v119, v119
	v_rcp_f32_e32 v118, v118
	v_add_f32_e32 v119, 1.0, v119
	v_rcp_f32_e32 v119, v119
	s_nop 0
	v_pk_mul_f32 v[102:103], v[104:105], v[118:119]
	s_nop 0
	v_pk_mul_f32 v[100:101], v[100:101], v[102:103]
	v_pk_fma_f32 v[102:103], v[134:135], v[108:109], v[116:117]
	v_cvt_pk_bf16_f32 v100, v100, v101
	v_pk_fma_f32 v[102:103], v[138:139], v[114:115], v[102:103]
	v_cndmask_b32_e64 v108, v83, v75, s[6:7]
	v_pk_mul_f32 v[116:117], v[84:85], v[144:145]
	v_mul_f32_e32 v104, 0xbfb8aa3b, v102
	v_exp_f32_e32 v104, v104
	v_mul_f32_e32 v105, 0xbfb8aa3b, v103
	v_exp_f32_e32 v105, v105
	v_pk_mul_f32 v[114:115], v[86:87], v[146:147]
	v_add_f32_e32 v101, 1.0, v104
	v_rcp_f32_e32 v104, v101
	v_add_f32_e32 v101, 1.0, v105
	v_rcp_f32_e32 v105, v101
	s_nop 0
	v_pk_mul_f32 v[102:103], v[102:103], v[104:105]
	s_nop 0
	v_pk_mul_f32 v[102:103], v[106:107], v[102:103]
	v_cndmask_b32_e64 v104, v81, v73, s[6:7]
	v_cvt_pk_bf16_f32 v101, v102, v103
	global_store_dwordx2 v[98:99], v[100:101], off
	v_cndmask_b32_e64 v100, v84, v92, s[4:5]
	v_cndmask_b32_e64 v101, v80, v72, s[6:7]
	s_nop 0
	v_mov_b32_dpp v92, v100 row_ror:1 row_mask:0xf bank_mask:0xf
	v_cndmask_b32_e64 v100, v80, v88, s[4:5]
	v_cndmask_b32_e64 v105, v86, v78, s[6:7]
	s_nop 0
	v_mov_b32_dpp v88, v100 row_ror:1 row_mask:0xf bank_mask:0xf
	v_cndmask_b32_e64 v100, v84, v76, s[6:7]
	v_cndmask_b32_e64 v107, v87, v79, s[6:7]
	s_nop 0
	v_mov_b32_dpp v102, v100 row_ror:15 row_mask:0xf bank_mask:0xf
	s_nop 1
	v_mov_b32_dpp v100, v101 row_ror:15 row_mask:0xf bank_mask:0xf
	v_cndmask_b32_e64 v101, v85, v93, s[4:5]
	s_nop 1
	v_mov_b32_dpp v93, v101 row_ror:1 row_mask:0xf bank_mask:0xf
	v_cndmask_b32_e64 v101, v81, v89, s[4:5]
	v_pk_fma_f32 v[92:93], v[120:121], v[92:93], v[116:117]
	v_cndmask_b32_e64 v116, v57, v49, s[6:7]
	v_mov_b32_dpp v89, v101 row_ror:1 row_mask:0xf bank_mask:0xf
	v_cndmask_b32_e64 v101, v85, v77, s[6:7]
	s_nop 0
	s_nop 0
	v_mov_b32_dpp v103, v101 row_ror:15 row_mask:0xf bank_mask:0xf
	v_pk_fma_f32 v[92:93], v[124:125], v[102:103], v[92:93]
	v_cndmask_b32_e64 v102, v75, v67, s[6:7]
	v_mov_b32_dpp v101, v104 row_ror:15 row_mask:0xf bank_mask:0xf
	v_cndmask_b32_e64 v104, v86, v94, s[4:5]
	v_pk_add_f32 v[92:93], v[128:129], v[92:93]
	s_nop 0
	v_mov_b32_dpp v94, v104 row_ror:1 row_mask:0xf bank_mask:0xf
	v_cndmask_b32_e64 v104, v82, v90, s[4:5]
	s_nop 1
	v_mov_b32_dpp v90, v104 row_ror:1 row_mask:0xf bank_mask:0xf
	s_nop 1
	v_mov_b32_dpp v104, v105 row_ror:15 row_mask:0xf bank_mask:0xf
	v_cndmask_b32_e64 v105, v82, v74, s[6:7]
	s_nop 1
	v_mov_b32_dpp v106, v105 row_ror:15 row_mask:0xf bank_mask:0xf
	v_cndmask_b32_e64 v105, v87, v95, s[4:5]
	s_nop 1
	v_mov_b32_dpp v95, v105 row_ror:1 row_mask:0xf bank_mask:0xf
	v_cndmask_b32_e64 v105, v83, v91, s[4:5]
	v_pk_fma_f32 v[94:95], v[122:123], v[94:95], v[114:115]
	s_nop 0
	v_mov_b32_dpp v91, v105 row_ror:1 row_mask:0xf bank_mask:0xf
	v_cndmask_b32_e64 v115, v61, v53, s[6:7]
	s_nop 0
	v_mov_b32_dpp v105, v107 row_ror:15 row_mask:0xf bank_mask:0xf
	v_pk_fma_f32 v[94:95], v[126:127], v[104:105], v[94:95]
	v_add_u32_e32 v104, s17, v202
	v_mov_b32_dpp v107, v108 row_ror:15 row_mask:0xf bank_mask:0xf
	v_pk_mul_f32 v[108:109], v[80:81], v[148:149]
	v_pk_add_f32 v[94:95], v[130:131], v[94:95]
	v_pk_fma_f32 v[88:89], v[132:133], v[88:89], v[108:109]
	v_pk_fma_f32 v[108:109], v[82:83], v[150:151], v[142:143]
	v_pk_fma_f32 v[88:89], v[136:137], v[100:101], v[88:89]
	v_pk_fma_f32 v[90:91], v[134:135], v[90:91], v[108:109]
	v_pk_add_f32 v[88:89], v[140:141], v[88:89]
	v_pk_fma_f32 v[90:91], v[138:139], v[106:107], v[90:91]
	v_mul_f32_e32 v100, 0xbfb8aa3b, v88
	v_exp_f32_e32 v111, v100
	v_mad_i64_i32 v[100:101], s[28:29], v110, s46, v[184:185]
	v_add_f32_e32 v110, 1.0, v111
	v_mul_f32_e32 v111, 0xbfb8aa3b, v89
	v_exp_f32_e32 v111, v111
	v_rcp_f32_e32 v110, v110
	v_lshl_add_u64 v[100:101], v[100:101], 0, v[186:187]
	v_pk_mul_f32 v[108:109], v[76:77], v[144:145]
	v_add_f32_e32 v111, 1.0, v111
	v_rcp_f32_e32 v111, v111
	v_pk_mul_f32 v[106:107], v[78:79], v[146:147]
	v_pk_mul_f32 v[88:89], v[88:89], v[110:111]
	s_nop 0
	v_pk_mul_f32 v[88:89], v[92:93], v[88:89]
	v_mul_f32_e32 v92, 0xbfb8aa3b, v90
	v_exp_f32_e32 v92, v92
	v_mul_f32_e32 v93, 0xbfb8aa3b, v91
	v_exp_f32_e32 v93, v93
	v_cvt_pk_bf16_f32 v88, v88, v89
	v_add_f32_e32 v89, 1.0, v92
	v_rcp_f32_e32 v92, v89
	v_add_f32_e32 v89, 1.0, v93
	v_rcp_f32_e32 v93, v89
	s_nop 0
	v_pk_mul_f32 v[90:91], v[90:91], v[92:93]
	s_nop 0
	v_pk_mul_f32 v[90:91], v[94:95], v[90:91]
; __device__ __forceinline__ void st_bf4(bf16_t* p, f32x4 v) { u32x2 w; w.x = pk2(v[0], v[1]); w.y = pk2(v[2], v[3]); *(u32x2*)p = w; }
; __device__ __forceinline__ float sigmoidf_(float x) { return __builtin_amdgcn_rcpf(1.f + __expf(-x)); }
; __device__ __forceinline__ float dpp_ror1(float v) { return __int_as_float(__builtin_amdgcn_update_dpp(0, __float_as_int(v), 0x121, 0xf, 0xf, false)); }
; __device__ __forceinline__ float dpp_rol1(float v) { return __int_as_float(__builtin_amdgcn_update_dpp(0, __float_as_int(v), 0x12F, 0xf, 0xf, false)); }
;     __device__ __forceinline__ void tile(const f32x4 (&acc)[2][2][4][2], const Unit& u, int wr, int wc, int fr, int fq) const {
;     ...
;         for (int n = 0; n < 2; ++n) {
;             const int cv = 128 * u.pn + 32 * wc + 16 * n + 4 * fq, cg = FF + cv;
;             const f32x4 wv0 = *(const f32x4*)(cw + cv), wv1 = *(const f32x4*)(cw + F2 + cv), wv2 = *(const f32x4*)(cw + 2 * F2 + cv), bv = *(const f32x4*)(cb + cv);
;             const f32x4 wg0 = *(const f32x4*)(cw + cg), wg1 = *(const f32x4*)(cw + F2 + cg), wg2 = *(const f32x4*)(cw + 2 * F2 + cg), bg = *(const f32x4*)(cb + cg);
; #pragma unroll
;             for (int ai = 0; ai < 2; ++ai)
; #pragma unroll
;                 for (int m = 0; m < 4; ++m) {
;                     f32x4 r;
; #pragma unroll
;                     for (int i = 0; i < 4; ++i) {
;                         const float xv = acc[ai][0][m][n][i], xg = acc[ai][1][m][n][i];
;                         const float uv = m > 0 ? acc[ai][0][m > 0 ? m - 1 : 0][n][i] : 0.f, ug = m > 0 ? acc[ai][1][m > 0 ? m - 1 : 0][n][i] : 0.f;
;                         const float dv = m < 3 ? acc[ai][0][m < 3 ? m + 1 : 3][n][i] : 0.f, dg = m < 3 ? acc[ai][1][m < 3 ? m + 1 : 3][n][i] : 0.f;
;                         const float pv = dpp_ror1(fr == 15 ? uv : xv), pg = dpp_ror1(fr == 15 ? ug : xg);
;                         const float nv = dpp_rol1(fr == 0 ? dv : xv), ng = dpp_rol1(fr == 0 ? dg : xg);
;                         const float yv = wv0[i] * pv + wv1[i] * xv + wv2[i] * nv + bv[i];
;                         const float yg = wg0[i] * pg + wg1[i] * xg + wg2[i] * ng + bg[i];
;                         r[i] = yg * sigmoidf_(yg) * yv;
;                     }
;                     st_bf4(ACT + (size_t)(u.pm * BM + ai * HALF + wr * 64 + m * 16 + fr) * FF + cv, r);
	v_cndmask_b32_e64 v92, v73, v65, s[6:7]
	v_cvt_pk_bf16_f32 v89, v90, v91
	global_store_dwordx2 v[100:101], v[88:89], off
	v_cndmask_b32_e64 v88, v76, v84, s[4:5]
	v_cndmask_b32_e64 v89, v76, v68, s[6:7]
	s_nop 0
	v_mov_b32_dpp v84, v88 row_ror:1 row_mask:0xf bank_mask:0xf
	v_cndmask_b32_e64 v88, v72, v80, s[4:5]
	v_cndmask_b32_e64 v91, v77, v69, s[6:7]
	v_cndmask_b32_e64 v93, v78, v70, s[6:7]
	v_mov_b32_dpp v80, v88 row_ror:1 row_mask:0xf bank_mask:0xf
	v_cndmask_b32_e64 v95, v79, v71, s[6:7]
	v_mov_b32_dpp v88, v89 row_ror:15 row_mask:0xf bank_mask:0xf
	v_cndmask_b32_e64 v89, v72, v64, s[6:7]
	s_nop 1
	v_mov_b32_dpp v90, v89 row_ror:15 row_mask:0xf bank_mask:0xf
	v_cndmask_b32_e64 v89, v77, v85, s[4:5]
	s_nop 1
	v_mov_b32_dpp v85, v89 row_ror:1 row_mask:0xf bank_mask:0xf
	v_cndmask_b32_e64 v89, v73, v81, s[4:5]
	v_pk_fma_f32 v[84:85], v[120:121], v[84:85], v[108:109]
	s_nop 0
	v_mov_b32_dpp v81, v89 row_ror:1 row_mask:0xf bank_mask:0xf
	s_nop 0
	v_mov_b32_dpp v89, v91 row_ror:15 row_mask:0xf bank_mask:0xf
	v_pk_fma_f32 v[84:85], v[124:125], v[88:89], v[84:85]
	v_cndmask_b32_e64 v88, v67, 0, s[6:7]
	v_mov_b32_dpp v91, v92 row_ror:15 row_mask:0xf bank_mask:0xf
	v_cndmask_b32_e64 v92, v78, v86, s[4:5]
	v_pk_add_f32 v[84:85], v[128:129], v[84:85]
	s_nop 0
	v_mov_b32_dpp v86, v92 row_ror:1 row_mask:0xf bank_mask:0xf
	v_cndmask_b32_e64 v92, v74, v82, s[4:5]
	s_nop 1
	v_mov_b32_dpp v82, v92 row_ror:1 row_mask:0xf bank_mask:0xf
	s_nop 1
	v_mov_b32_dpp v92, v93 row_ror:15 row_mask:0xf bank_mask:0xf
	v_cndmask_b32_e64 v93, v74, v66, s[6:7]
	s_nop 1
	v_mov_b32_dpp v94, v93 row_ror:15 row_mask:0xf bank_mask:0xf
	v_cndmask_b32_e64 v93, v79, v87, s[4:5]
	s_nop 1
	v_mov_b32_dpp v87, v93 row_ror:1 row_mask:0xf bank_mask:0xf
	v_cndmask_b32_e64 v93, v75, v83, s[4:5]
	v_pk_fma_f32 v[86:87], v[122:123], v[86:87], v[106:107]
	s_nop 0
	v_mov_b32_dpp v83, v93 row_ror:1 row_mask:0xf bank_mask:0xf
	s_nop 0
	v_mov_b32_dpp v93, v95 row_ror:15 row_mask:0xf bank_mask:0xf
	v_pk_fma_f32 v[86:87], v[126:127], v[92:93], v[86:87]
	v_mov_b32_dpp v106, v60 row_shr:1 row_mask:0xf bank_mask:0xf bound_ctrl:1
	v_mov_b32_dpp v95, v102 row_ror:15 row_mask:0xf bank_mask:0xf
	v_pk_fma_f32 v[102:103], v[72:73], v[148:149], v[140:141]
	v_pk_add_f32 v[86:87], v[130:131], v[86:87]
	v_pk_fma_f32 v[80:81], v[132:133], v[80:81], v[102:103]
	s_nop 0
	v_pk_fma_f32 v[80:81], v[136:137], v[90:91], v[80:81]
	s_nop 0
	v_mov_b32_dpp v108, v56 row_shr:1 row_mask:0xf bank_mask:0xf bound_ctrl:1
	v_mul_f32_e32 v90, 0xbfb8aa3b, v80
	v_exp_f32_e32 v105, v90
	v_mad_i64_i32 v[90:91], s[28:29], v104, s46, v[184:185]
	v_lshl_add_u64 v[102:103], v[90:91], 0, v[186:187]
	v_add_f32_e32 v104, 1.0, v105
	v_mul_f32_e32 v105, 0xbfb8aa3b, v81
	v_exp_f32_e32 v105, v105
	v_rcp_f32_e32 v104, v104
	v_pk_fma_f32 v[90:91], v[74:75], v[150:151], v[142:143]
	v_cndmask_b32_e64 v107, v60, v52, s[6:7]
	v_add_f32_e32 v105, 1.0, v105
	v_rcp_f32_e32 v105, v105
	v_pk_fma_f32 v[82:83], v[134:135], v[82:83], v[90:91]
	v_mov_b32_dpp v110, v107 row_ror:15 row_mask:0xf bank_mask:0xf
	v_pk_fma_f32 v[82:83], v[138:139], v[94:95], v[82:83]
	v_pk_mul_f32 v[80:81], v[80:81], v[104:105]
	s_nop 0
	v_pk_mul_f32 v[80:81], v[84:85], v[80:81]
	v_mul_f32_e32 v84, 0xbfb8aa3b, v82
	v_exp_f32_e32 v84, v84
	v_mul_f32_e32 v85, 0xbfb8aa3b, v83
	v_exp_f32_e32 v85, v85
	v_cvt_pk_bf16_f32 v80, v80, v81
	v_add_f32_e32 v81, 1.0, v84
	v_rcp_f32_e32 v84, v81
	v_add_f32_e32 v81, 1.0, v85
	v_rcp_f32_e32 v85, v81
	v_cndmask_b32_e64 v107, v56, v48, s[6:7]
	v_pk_mul_f32 v[82:83], v[82:83], v[84:85]
	s_nop 0
	v_pk_mul_f32 v[82:83], v[86:87], v[82:83]
	v_cndmask_b32_e64 v84, v65, 0, s[6:7]
	v_cvt_pk_bf16_f32 v81, v82, v83
	global_store_dwordx2 v[102:103], v[80:81], off
	v_cndmask_b32_e64 v80, v68, v76, s[4:5]
	s_nop 1
	v_mov_b32_dpp v76, v80 row_ror:1 row_mask:0xf bank_mask:0xf
	v_cndmask_b32_e64 v80, v64, v72, s[4:5]
	v_cndmask_b32_e64 v83, v69, 0, s[6:7]
	s_nop 0
	v_mov_b32_dpp v72, v80 row_ror:1 row_mask:0xf bank_mask:0xf
	v_cndmask_b32_e64 v87, v71, 0, s[6:7]
	v_mov_b32_dpp v80, v68 row_shl:1 row_mask:0xf bank_mask:0xf bound_ctrl:1
	v_mov_b32_dpp v114, v107 row_ror:15 row_mask:0xf bank_mask:0xf
	v_mov_b32_dpp v82, v64 row_shl:1 row_mask:0xf bank_mask:0xf bound_ctrl:1
	v_cndmask_b32_e64 v81, v69, v77, s[4:5]
	v_pk_mul_f32 v[68:69], v[68:69], v[144:145]
	v_mov_b32_dpp v107, v61 row_shr:1 row_mask:0xf bank_mask:0xf bound_ctrl:1
	v_mov_b32_dpp v77, v81 row_ror:1 row_mask:0xf bank_mask:0xf
	v_cndmask_b32_e64 v81, v65, v73, s[4:5]
	v_pk_mul_f32 v[64:65], v[64:65], v[148:149]
	v_pk_fma_f32 v[68:69], v[120:121], v[76:77], v[68:69]
	v_mov_b32_dpp v73, v81 row_ror:1 row_mask:0xf bank_mask:0xf
	v_pk_fma_f32 v[64:65], v[132:133], v[72:73], v[64:65]
	v_mov_b32_dpp v81, v83 row_ror:15 row_mask:0xf bank_mask:0xf
	v_pk_fma_f32 v[68:69], v[124:125], v[80:81], v[68:69]
	v_mov_b32_dpp v109, v57 row_shr:1 row_mask:0xf bank_mask:0xf bound_ctrl:1
	v_mov_b32_dpp v83, v84 row_ror:15 row_mask:0xf bank_mask:0xf
	v_cndmask_b32_e64 v84, v70, v78, s[4:5]
	v_pk_fma_f32 v[64:65], v[136:137], v[82:83], v[64:65]
	v_pk_add_f32 v[68:69], v[128:129], v[68:69]
	v_mov_b32_dpp v78, v84 row_ror:1 row_mask:0xf bank_mask:0xf
	v_cndmask_b32_e64 v84, v66, v74, s[4:5]
	v_pk_add_f32 v[64:65], v[140:141], v[64:65]
	s_nop 0
	v_mov_b32_dpp v74, v84 row_ror:1 row_mask:0xf bank_mask:0xf
	v_mul_f32_e32 v72, 0xbfb8aa3b, v64
	v_exp_f32_e32 v82, v72
	v_mov_b32_dpp v84, v70 row_shl:1 row_mask:0xf bank_mask:0xf bound_ctrl:1
	v_mov_b32_dpp v111, v115 row_ror:15 row_mask:0xf bank_mask:0xf
	v_mov_b32_dpp v86, v66 row_shl:1 row_mask:0xf bank_mask:0xf bound_ctrl:1
	v_cndmask_b32_e64 v85, v71, v79, s[4:5]
; __device__ __forceinline__ void st_bf4(bf16_t* p, f32x4 v) { u32x2 w; w.x = pk2(v[0], v[1]); w.y = pk2(v[2], v[3]); *(u32x2*)p = w; }
; __device__ __forceinline__ float sigmoidf_(float x) { return __builtin_amdgcn_rcpf(1.f + __expf(-x)); }
; __device__ __forceinline__ float dpp_ror1(float v) { return __int_as_float(__builtin_amdgcn_update_dpp(0, __float_as_int(v), 0x121, 0xf, 0xf, false)); }
; __device__ __forceinline__ float dpp_rol1(float v) { return __int_as_float(__builtin_amdgcn_update_dpp(0, __float_as_int(v), 0x12F, 0xf, 0xf, false)); }
;     __device__ __forceinline__ void tile(const f32x4 (&acc)[2][2][4][2], const Unit& u, int wr, int wc, int fr, int fq) const {
;     ...
;         for (int n = 0; n < 2; ++n) {
;             const int cv = 128 * u.pn + 32 * wc + 16 * n + 4 * fq, cg = FF + cv;
;             const f32x4 wv0 = *(const f32x4*)(cw + cv), wv1 = *(const f32x4*)(cw + F2 + cv), wv2 = *(const f32x4*)(cw + 2 * F2 + cv), bv = *(const f32x4*)(cb + cv);
;             const f32x4 wg0 = *(const f32x4*)(cw + cg), wg1 = *(const f32x4*)(cw + F2 + cg), wg2 = *(const f32x4*)(cw + 2 * F2 + cg), bg = *(const f32x4*)(cb + cg);
; #pragma unroll
;             for (int ai = 0; ai < 2; ++ai)
; #pragma unroll
;                 for (int m = 0; m < 4; ++m) {
;                     f32x4 r;
; #pragma unroll
;                     for (int i = 0; i < 4; ++i) {
;                         const float xv = acc[ai][0][m][n][i], xg = acc[ai][1][m][n][i];
;                         const float uv = m > 0 ? acc[ai][0][m > 0 ? m - 1 : 0][n][i] : 0.f, ug = m > 0 ? acc[ai][1][m > 0 ? m - 1 : 0][n][i] : 0.f;
;                         const float dv = m < 3 ? acc[ai][0][m < 3 ? m + 1 : 3][n][i] : 0.f, dg = m < 3 ? acc[ai][1][m < 3 ? m + 1 : 3][n][i] : 0.f;
;                         const float pv = dpp_ror1(fr == 15 ? uv : xv), pg = dpp_ror1(fr == 15 ? ug : xg);
;                         const float nv = dpp_rol1(fr == 0 ? dv : xv), ng = dpp_rol1(fr == 0 ? dg : xg);
;                         const float yv = wv0[i] * pv + wv1[i] * xv + wv2[i] * nv + bv[i];
;                         const float yg = wg0[i] * pg + wg1[i] * xg + wg2[i] * ng + bg[i];
;                         r[i] = yg * sigmoidf_(yg) * yv;
;                     }
;                     st_bf4(ACT + (size_t)(u.pm * BM + ai * HALF + wr * 64 + m * 16 + fr) * FF + cv, r);
	v_pk_mul_f32 v[70:71], v[70:71], v[146:147]
	v_mov_b32_dpp v115, v116 row_ror:15 row_mask:0xf bank_mask:0xf
	v_mov_b32_dpp v79, v85 row_ror:1 row_mask:0xf bank_mask:0xf
	v_cndmask_b32_e64 v85, v67, v75, s[4:5]
	v_pk_mul_f32 v[66:67], v[66:67], v[150:151]
	v_pk_fma_f32 v[70:71], v[122:123], v[78:79], v[70:71]
	v_mov_b32_dpp v75, v85 row_ror:1 row_mask:0xf bank_mask:0xf
	v_pk_fma_f32 v[66:67], v[134:135], v[74:75], v[66:67]
	v_mov_b32_dpp v85, v87 row_ror:15 row_mask:0xf bank_mask:0xf
	v_pk_fma_f32 v[70:71], v[126:127], v[84:85], v[70:71]
	v_mov_b32_dpp v116, v62 row_shr:1 row_mask:0xf bank_mask:0xf bound_ctrl:1
	v_mov_b32_dpp v87, v88 row_ror:15 row_mask:0xf bank_mask:0xf
	v_add_u32_e32 v88, s17, v203
	v_mad_i64_i32 v[72:73], s[28:29], v88, s46, v[184:185]
	v_lshl_add_u64 v[104:105], v[72:73], 0, v[186:187]
	v_mul_f32_e32 v73, 0xbfb8aa3b, v65
	v_exp_f32_e32 v73, v73
	v_add_f32_e32 v72, 1.0, v82
	v_rcp_f32_e32 v72, v72
	v_pk_fma_f32 v[66:67], v[138:139], v[86:87], v[66:67]
	v_add_f32_e32 v73, 1.0, v73
	v_rcp_f32_e32 v73, v73
	v_pk_add_f32 v[66:67], v[142:143], v[66:67]
	v_pk_add_f32 v[70:71], v[130:131], v[70:71]
	v_pk_mul_f32 v[64:65], v[64:65], v[72:73]
	s_nop 0
	v_pk_mul_f32 v[64:65], v[68:69], v[64:65]
	v_mul_f32_e32 v68, 0xbfb8aa3b, v66
	v_exp_f32_e32 v68, v68
	v_mul_f32_e32 v69, 0xbfb8aa3b, v67
	v_exp_f32_e32 v69, v69
	v_cvt_pk_bf16_f32 v64, v64, v65
	v_add_f32_e32 v65, 1.0, v68
	v_rcp_f32_e32 v68, v65
	v_add_f32_e32 v65, 1.0, v69
	v_rcp_f32_e32 v69, v65
	v_mov_b32_dpp v118, v58 row_shr:1 row_mask:0xf bank_mask:0xf bound_ctrl:1
	v_cndmask_b32_e64 v117, v62, v54, s[6:7]
	v_pk_mul_f32 v[66:67], v[66:67], v[68:69]
	s_nop 0
	v_mov_b32_dpp v120, v117 row_ror:15 row_mask:0xf bank_mask:0xf
	v_pk_mul_f32 v[66:67], v[70:71], v[66:67]
	v_cndmask_b32_e64 v117, v58, v50, s[6:7]
	v_cvt_pk_bf16_f32 v65, v66, v67
	global_store_dwordx2 v[104:105], v[64:65], off
	v_mov_b32_dpp v122, v117 row_ror:15 row_mask:0xf bank_mask:0xf
	v_cndmask_b32_e64 v123, v63, v55, s[6:7]
	v_mov_b32_dpp v117, v63 row_shr:1 row_mask:0xf bank_mask:0xf bound_ctrl:1
	v_cndmask_b32_e64 v126, v59, v51, s[6:7]
	v_pk_fma_f32 v[124:125], v[56:57], v[234:235], v[242:243]
	s_nop 0
	v_pk_fma_f32 v[108:109], v[230:231], v[108:109], v[124:125]
	v_mov_b32_dpp v119, v59 row_shr:1 row_mask:0xf bank_mask:0xf bound_ctrl:1
	v_pk_fma_f32 v[108:109], v[238:239], v[114:115], v[108:109]
	v_pk_fma_f32 v[128:129], v[60:61], v[246:247], v[180:181]
	v_mul_f32_e32 v114, 0xbfb8aa3b, v108
	v_mul_f32_e32 v125, 0xbfb8aa3b, v109
	v_exp_f32_e32 v124, v114
	v_exp_f32_e32 v125, v125
	v_pk_fma_f32 v[106:107], v[250:251], v[106:107], v[128:129]
	v_mov_b32_dpp v121, v123 row_ror:15 row_mask:0xf bank_mask:0xf
	v_add_f32_e32 v124, 1.0, v124
	v_add_f32_e32 v125, 1.0, v125
	v_rcp_f32_e32 v124, v124
	v_rcp_f32_e32 v125, v125
	v_pk_fma_f32 v[106:107], v[190:191], v[110:111], v[106:107]
	v_pk_fma_f32 v[114:115], v[58:59], v[236:237], v[244:245]
	v_pk_mul_f32 v[108:109], v[108:109], v[124:125]
	v_mov_b32_dpp v123, v126 row_ror:15 row_mask:0xf bank_mask:0xf
	v_pk_mul_f32 v[106:107], v[106:107], v[108:109]
	v_pk_fma_f32 v[108:109], v[232:233], v[118:119], v[114:115]
	v_cvt_pk_bf16_f32 v106, v106, v107
	v_pk_fma_f32 v[108:109], v[240:241], v[122:123], v[108:109]
	v_pk_fma_f32 v[126:127], v[62:63], v[248:249], v[182:183]
	s_nop 0
	v_pk_fma_f32 v[114:115], v[252:253], v[116:117], v[126:127]
	v_mul_f32_e32 v110, 0xbfb8aa3b, v108
	v_exp_f32_e32 v110, v110
	v_mul_f32_e32 v111, 0xbfb8aa3b, v109
	v_exp_f32_e32 v111, v111
	v_pk_fma_f32 v[114:115], v[192:193], v[120:121], v[114:115]
	v_add_f32_e32 v107, 1.0, v110
	v_rcp_f32_e32 v110, v107
	v_add_f32_e32 v107, 1.0, v111
	v_rcp_f32_e32 v111, v107
	v_pk_fma_f32 v[116:117], v[48:49], v[234:235], v[242:243]
	v_cndmask_b32_e64 v118, v51, v43, s[6:7]
	v_pk_mul_f32 v[108:109], v[108:109], v[110:111]
	v_cndmask_b32_e64 v110, v49, v41, s[6:7]
	v_pk_mul_f32 v[108:109], v[114:115], v[108:109]
	v_cndmask_b32_e64 v111, v54, v46, s[6:7]
	v_cvt_pk_bf16_f32 v107, v108, v109
	global_store_dwordx2 v[168:169], v[106:107], off offset:32
	v_cndmask_b32_e64 v106, v52, v60, s[4:5]
	v_cndmask_b32_e64 v107, v52, v44, s[6:7]
	s_nop 0
	v_mov_b32_dpp v60, v106 row_ror:1 row_mask:0xf bank_mask:0xf
	v_cndmask_b32_e64 v106, v48, v56, s[4:5]
	v_cndmask_b32_e64 v109, v53, v45, s[6:7]
	s_nop 0
	v_mov_b32_dpp v56, v106 row_ror:1 row_mask:0xf bank_mask:0xf
	v_cndmask_b32_e64 v115, v55, v47, s[6:7]
	v_pk_fma_f32 v[120:121], v[52:53], v[246:247], v[180:181]
	v_mov_b32_dpp v106, v107 row_ror:15 row_mask:0xf bank_mask:0xf
	v_cndmask_b32_e64 v107, v48, v40, s[6:7]
	s_nop 1
	v_mov_b32_dpp v108, v107 row_ror:15 row_mask:0xf bank_mask:0xf
	v_cndmask_b32_e64 v107, v53, v61, s[4:5]
	s_nop 1
	v_mov_b32_dpp v61, v107 row_ror:1 row_mask:0xf bank_mask:0xf
	v_cndmask_b32_e64 v107, v49, v57, s[4:5]
	v_pk_fma_f32 v[60:61], v[250:251], v[60:61], v[120:121]
	s_nop 0
	v_mov_b32_dpp v57, v107 row_ror:1 row_mask:0xf bank_mask:0xf
	v_pk_fma_f32 v[56:57], v[230:231], v[56:57], v[116:117]
	s_nop 0
	v_mov_b32_dpp v107, v109 row_ror:15 row_mask:0xf bank_mask:0xf
	v_pk_fma_f32 v[60:61], v[190:191], v[106:107], v[60:61]
	v_pk_fma_f32 v[106:107], v[40:41], v[234:235], v[242:243]
	v_mov_b32_dpp v109, v110 row_ror:15 row_mask:0xf bank_mask:0xf
	v_pk_fma_f32 v[56:57], v[238:239], v[108:109], v[56:57]
	v_cndmask_b32_e64 v110, v54, v62, s[4:5]
	v_mul_f32_e32 v108, 0xbfb8aa3b, v56
	v_mul_f32_e32 v117, 0xbfb8aa3b, v57
	v_mov_b32_dpp v62, v110 row_ror:1 row_mask:0xf bank_mask:0xf
	v_cndmask_b32_e64 v110, v50, v58, s[4:5]
	v_exp_f32_e32 v116, v108
	v_exp_f32_e32 v117, v117
	v_mov_b32_dpp v58, v110 row_ror:1 row_mask:0xf bank_mask:0xf
	v_add_f32_e32 v116, 1.0, v116
; __device__ __forceinline__ void st_bf4(bf16_t* p, f32x4 v) { u32x2 w; w.x = pk2(v[0], v[1]); w.y = pk2(v[2], v[3]); *(u32x2*)p = w; }
; __device__ __forceinline__ float sigmoidf_(float x) { return __builtin_amdgcn_rcpf(1.f + __expf(-x)); }
; __device__ __forceinline__ float dpp_ror1(float v) { return __int_as_float(__builtin_amdgcn_update_dpp(0, __float_as_int(v), 0x121, 0xf, 0xf, false)); }
; __device__ __forceinline__ float dpp_rol1(float v) { return __int_as_float(__builtin_amdgcn_update_dpp(0, __float_as_int(v), 0x12F, 0xf, 0xf, false)); }
;     __device__ __forceinline__ void tile(const f32x4 (&acc)[2][2][4][2], const Unit& u, int wr, int wc, int fr, int fq) const {
;     ...
;         for (int n = 0; n < 2; ++n) {
;             const int cv = 128 * u.pn + 32 * wc + 16 * n + 4 * fq, cg = FF + cv;
;             const f32x4 wv0 = *(const f32x4*)(cw + cv), wv1 = *(const f32x4*)(cw + F2 + cv), wv2 = *(const f32x4*)(cw + 2 * F2 + cv), bv = *(const f32x4*)(cb + cv);
;             const f32x4 wg0 = *(const f32x4*)(cw + cg), wg1 = *(const f32x4*)(cw + F2 + cg), wg2 = *(const f32x4*)(cw + 2 * F2 + cg), bg = *(const f32x4*)(cb + cg);
; #pragma unroll
;             for (int ai = 0; ai < 2; ++ai)
; #pragma unroll
;                 for (int m = 0; m < 4; ++m) {
;                     f32x4 r;
; #pragma unroll
;                     for (int i = 0; i < 4; ++i) {
;                         const float xv = acc[ai][0][m][n][i], xg = acc[ai][1][m][n][i];
;                         const float uv = m > 0 ? acc[ai][0][m > 0 ? m - 1 : 0][n][i] : 0.f, ug = m > 0 ? acc[ai][1][m > 0 ? m - 1 : 0][n][i] : 0.f;
;                         const float dv = m < 3 ? acc[ai][0][m < 3 ? m + 1 : 3][n][i] : 0.f, dg = m < 3 ? acc[ai][1][m < 3 ? m + 1 : 3][n][i] : 0.f;
;                         const float pv = dpp_ror1(fr == 15 ? uv : xv), pg = dpp_ror1(fr == 15 ? ug : xg);
;                         const float nv = dpp_rol1(fr == 0 ? dv : xv), ng = dpp_rol1(fr == 0 ? dg : xg);
;                         const float yv = wv0[i] * pv + wv1[i] * xv + wv2[i] * nv + bv[i];
;                         const float yg = wg0[i] * pg + wg1[i] * xg + wg2[i] * ng + bg[i];
;                         r[i] = yg * sigmoidf_(yg) * yv;
;                     }
;                     st_bf4(ACT + (size_t)(u.pm * BM + ai * HALF + wr * 64 + m * 16 + fr) * FF + cv, r);
	v_add_f32_e32 v117, 1.0, v117
	v_mov_b32_dpp v110, v111 row_ror:15 row_mask:0xf bank_mask:0xf
	v_cndmask_b32_e64 v111, v50, v42, s[6:7]
	v_rcp_f32_e32 v116, v116
	v_rcp_f32_e32 v117, v117
	v_mov_b32_dpp v114, v111 row_ror:15 row_mask:0xf bank_mask:0xf
	v_cndmask_b32_e64 v111, v55, v63, s[4:5]
	v_pk_mul_f32 v[108:109], v[50:51], v[236:237]
	s_nop 0
	v_mov_b32_dpp v63, v111 row_ror:1 row_mask:0xf bank_mask:0xf
	v_cndmask_b32_e64 v111, v51, v59, s[4:5]
	v_pk_mul_f32 v[56:57], v[56:57], v[116:117]
	s_nop 0
	v_mov_b32_dpp v59, v111 row_ror:1 row_mask:0xf bank_mask:0xf
	v_pk_fma_f32 v[58:59], v[232:233], v[58:59], v[108:109]
	v_pk_mul_f32 v[56:57], v[60:61], v[56:57]
	v_mov_b32_dpp v111, v115 row_ror:15 row_mask:0xf bank_mask:0xf
	v_cvt_pk_bf16_f32 v56, v56, v57
	v_cndmask_b32_e64 v108, v43, v35, s[6:7]
	v_mov_b32_dpp v115, v118 row_ror:15 row_mask:0xf bank_mask:0xf
	v_pk_fma_f32 v[58:59], v[240:241], v[114:115], v[58:59]
	v_pk_fma_f32 v[118:119], v[54:55], v[248:249], v[182:183]
	v_pk_add_f32 v[58:59], v[244:245], v[58:59]
	v_pk_fma_f32 v[62:63], v[252:253], v[62:63], v[118:119]
	v_mul_f32_e32 v60, 0xbfb8aa3b, v58
	v_exp_f32_e32 v60, v60
	v_mul_f32_e32 v61, 0xbfb8aa3b, v59
	v_exp_f32_e32 v61, v61
	v_pk_fma_f32 v[62:63], v[192:193], v[110:111], v[62:63]
	v_add_f32_e32 v57, 1.0, v60
	v_rcp_f32_e32 v60, v57
	v_add_f32_e32 v57, 1.0, v61
	v_rcp_f32_e32 v61, v57
	v_pk_fma_f32 v[110:111], v[44:45], v[246:247], v[180:181]
	v_pk_mul_f32 v[58:59], v[58:59], v[60:61]
	s_nop 0
	v_pk_mul_f32 v[58:59], v[62:63], v[58:59]
	v_cndmask_b32_e64 v60, v41, v33, s[6:7]
	v_cvt_pk_bf16_f32 v57, v58, v59
	global_store_dwordx2 v[152:153], v[56:57], off offset:32
	v_cndmask_b32_e64 v56, v44, v52, s[4:5]
	v_cndmask_b32_e64 v57, v44, v36, s[6:7]
	s_nop 0
	v_mov_b32_dpp v52, v56 row_ror:1 row_mask:0xf bank_mask:0xf
	v_cndmask_b32_e64 v56, v40, v48, s[4:5]
	v_cndmask_b32_e64 v59, v45, v37, s[6:7]
	v_cndmask_b32_e64 v61, v46, v38, s[6:7]
	v_mov_b32_dpp v48, v56 row_ror:1 row_mask:0xf bank_mask:0xf
	v_cndmask_b32_e64 v63, v47, v39, s[6:7]
	v_mov_b32_dpp v56, v57 row_ror:15 row_mask:0xf bank_mask:0xf
	v_cndmask_b32_e64 v57, v40, v32, s[6:7]
	s_nop 1
	v_mov_b32_dpp v58, v57 row_ror:15 row_mask:0xf bank_mask:0xf
	v_cndmask_b32_e64 v57, v45, v53, s[4:5]
	s_nop 1
	v_mov_b32_dpp v53, v57 row_ror:1 row_mask:0xf bank_mask:0xf
	v_cndmask_b32_e64 v57, v41, v49, s[4:5]
	v_pk_fma_f32 v[52:53], v[250:251], v[52:53], v[110:111]
	s_nop 0
	v_mov_b32_dpp v49, v57 row_ror:1 row_mask:0xf bank_mask:0xf
	v_pk_fma_f32 v[48:49], v[230:231], v[48:49], v[106:107]
	s_nop 0
	v_mov_b32_dpp v57, v59 row_ror:15 row_mask:0xf bank_mask:0xf
	v_pk_fma_f32 v[52:53], v[190:191], v[56:57], v[52:53]
	v_cndmask_b32_e64 v56, v35, 0, s[6:7]
	v_mov_b32_dpp v59, v60 row_ror:15 row_mask:0xf bank_mask:0xf
	v_pk_fma_f32 v[48:49], v[238:239], v[58:59], v[48:49]
	v_cndmask_b32_e64 v60, v46, v54, s[4:5]
	v_mul_f32_e32 v58, 0xbfb8aa3b, v48
	v_mul_f32_e32 v107, 0xbfb8aa3b, v49
	v_mov_b32_dpp v54, v60 row_ror:1 row_mask:0xf bank_mask:0xf
	v_cndmask_b32_e64 v60, v42, v50, s[4:5]
	v_exp_f32_e32 v106, v58
	v_exp_f32_e32 v107, v107
	v_mov_b32_dpp v50, v60 row_ror:1 row_mask:0xf bank_mask:0xf
	v_add_f32_e32 v106, 1.0, v106
	v_add_f32_e32 v107, 1.0, v107
	v_mov_b32_dpp v60, v61 row_ror:15 row_mask:0xf bank_mask:0xf
	v_cndmask_b32_e64 v61, v42, v34, s[6:7]
	v_rcp_f32_e32 v106, v106
	v_rcp_f32_e32 v107, v107
	v_mov_b32_dpp v62, v61 row_ror:15 row_mask:0xf bank_mask:0xf
	v_cndmask_b32_e64 v61, v47, v55, s[4:5]
	v_pk_fma_f32 v[58:59], v[42:43], v[236:237], v[244:245]
	s_nop 0
	v_mov_b32_dpp v55, v61 row_ror:1 row_mask:0xf bank_mask:0xf
	v_cndmask_b32_e64 v61, v43, v51, s[4:5]
	v_pk_mul_f32 v[48:49], v[48:49], v[106:107]
	s_nop 0
	v_mov_b32_dpp v51, v61 row_ror:1 row_mask:0xf bank_mask:0xf
	v_pk_fma_f32 v[50:51], v[232:233], v[50:51], v[58:59]
	v_pk_mul_f32 v[48:49], v[52:53], v[48:49]
	v_mov_b32_dpp v61, v63 row_ror:15 row_mask:0xf bank_mask:0xf
	v_cvt_pk_bf16_f32 v48, v48, v49
	s_nop 0
	v_mov_b32_dpp v63, v108 row_ror:15 row_mask:0xf bank_mask:0xf
	v_pk_fma_f32 v[50:51], v[240:241], v[62:63], v[50:51]
	v_pk_fma_f32 v[108:109], v[46:47], v[248:249], v[182:183]
	s_nop 0
	v_pk_fma_f32 v[54:55], v[252:253], v[54:55], v[108:109]
	v_mul_f32_e32 v52, 0xbfb8aa3b, v50
	v_exp_f32_e32 v52, v52
	v_mul_f32_e32 v53, 0xbfb8aa3b, v51
	v_exp_f32_e32 v53, v53
	v_pk_fma_f32 v[54:55], v[192:193], v[60:61], v[54:55]
	v_add_f32_e32 v49, 1.0, v52
	v_rcp_f32_e32 v52, v49
	v_add_f32_e32 v49, 1.0, v53
	v_rcp_f32_e32 v53, v49
	s_nop 0
	v_pk_mul_f32 v[50:51], v[50:51], v[52:53]
	s_nop 0
	v_pk_mul_f32 v[50:51], v[54:55], v[50:51]
	v_cndmask_b32_e64 v52, v33, 0, s[6:7]
	v_cvt_pk_bf16_f32 v49, v50, v51
	global_store_dwordx2 v[112:113], v[48:49], off offset:32
	v_cndmask_b32_e64 v48, v36, v44, s[4:5]
	s_nop 1
	v_mov_b32_dpp v44, v48 row_ror:1 row_mask:0xf bank_mask:0xf
	v_cndmask_b32_e64 v48, v32, v40, s[4:5]
	v_cndmask_b32_e64 v51, v37, 0, s[6:7]
	s_nop 0
	v_mov_b32_dpp v40, v48 row_ror:1 row_mask:0xf bank_mask:0xf
	v_mov_b32_dpp v48, v36 row_shl:1 row_mask:0xf bank_mask:0xf bound_ctrl:1
	s_nop 1
	v_mov_b32_dpp v50, v32 row_shl:1 row_mask:0xf bank_mask:0xf bound_ctrl:1
	v_cndmask_b32_e64 v49, v37, v45, s[4:5]
	v_pk_mul_f32 v[36:37], v[36:37], v[246:247]
	s_nop 0
	v_mov_b32_dpp v45, v49 row_ror:1 row_mask:0xf bank_mask:0xf
	v_cndmask_b32_e64 v49, v33, v41, s[4:5]
	v_pk_mul_f32 v[32:33], v[32:33], v[234:235]
	v_pk_fma_f32 v[36:37], v[250:251], v[44:45], v[36:37]
	v_mov_b32_dpp v41, v49 row_ror:1 row_mask:0xf bank_mask:0xf
	v_pk_fma_f32 v[32:33], v[230:231], v[40:41], v[32:33]
	v_mov_b32_dpp v49, v51 row_ror:15 row_mask:0xf bank_mask:0xf
; __device__ __forceinline__ void st_bf4(bf16_t* p, f32x4 v) { u32x2 w; w.x = pk2(v[0], v[1]); w.y = pk2(v[2], v[3]); *(u32x2*)p = w; }
; __device__ __forceinline__ float sigmoidf_(float x) { return __builtin_amdgcn_rcpf(1.f + __expf(-x)); }
; __device__ __forceinline__ float dpp_ror1(float v) { return __int_as_float(__builtin_amdgcn_update_dpp(0, __float_as_int(v), 0x121, 0xf, 0xf, false)); }
; __device__ __forceinline__ float dpp_rol1(float v) { return __int_as_float(__builtin_amdgcn_update_dpp(0, __float_as_int(v), 0x12F, 0xf, 0xf, false)); }
;     __device__ __forceinline__ void tile(const f32x4 (&acc)[2][2][4][2], const Unit& u, int wr, int wc, int fr, int fq) const {
;     ...
;         for (int n = 0; n < 2; ++n) {
;             const int cv = 128 * u.pn + 32 * wc + 16 * n + 4 * fq, cg = FF + cv;
;             const f32x4 wv0 = *(const f32x4*)(cw + cv), wv1 = *(const f32x4*)(cw + F2 + cv), wv2 = *(const f32x4*)(cw + 2 * F2 + cv), bv = *(const f32x4*)(cb + cv);
;             const f32x4 wg0 = *(const f32x4*)(cw + cg), wg1 = *(const f32x4*)(cw + F2 + cg), wg2 = *(const f32x4*)(cw + 2 * F2 + cg), bg = *(const f32x4*)(cb + cg);
; #pragma unroll
;             for (int ai = 0; ai < 2; ++ai)
; #pragma unroll
;                 for (int m = 0; m < 4; ++m) {
;                     f32x4 r;
; #pragma unroll
;                     for (int i = 0; i < 4; ++i) {
;                         const float xv = acc[ai][0][m][n][i], xg = acc[ai][1][m][n][i];
;                         const float uv = m > 0 ? acc[ai][0][m > 0 ? m - 1 : 0][n][i] : 0.f, ug = m > 0 ? acc[ai][1][m > 0 ? m - 1 : 0][n][i] : 0.f;
;                         const float dv = m < 3 ? acc[ai][0][m < 3 ? m + 1 : 3][n][i] : 0.f, dg = m < 3 ? acc[ai][1][m < 3 ? m + 1 : 3][n][i] : 0.f;
;                         const float pv = dpp_ror1(fr == 15 ? uv : xv), pg = dpp_ror1(fr == 15 ? ug : xg);
;                         const float nv = dpp_rol1(fr == 0 ? dv : xv), ng = dpp_rol1(fr == 0 ? dg : xg);
;                         const float yv = wv0[i] * pv + wv1[i] * xv + wv2[i] * nv + bv[i];
;                         const float yg = wg0[i] * pg + wg1[i] * xg + wg2[i] * ng + bg[i];
;                         r[i] = yg * sigmoidf_(yg) * yv;
;                     }
;                     st_bf4(ACT + (size_t)(u.pm * BM + ai * HALF + wr * 64 + m * 16 + fr) * FF + cv, r);
	v_pk_fma_f32 v[36:37], v[190:191], v[48:49], v[36:37]
	v_pk_fma_f32 v[48:49], v[24:25], v[234:235], v[242:243]
	v_mov_b32_dpp v51, v52 row_ror:15 row_mask:0xf bank_mask:0xf
	v_pk_fma_f32 v[32:33], v[238:239], v[50:51], v[32:33]
	v_cndmask_b32_e64 v52, v38, v46, s[4:5]
	v_pk_add_f32 v[32:33], v[242:243], v[32:33]
	s_nop 0
	v_mul_f32_e32 v40, 0xbfb8aa3b, v32
	v_mul_f32_e32 v41, 0xbfb8aa3b, v33
	v_mov_b32_dpp v46, v52 row_ror:1 row_mask:0xf bank_mask:0xf
	v_cndmask_b32_e64 v52, v34, v42, s[4:5]
	v_exp_f32_e32 v40, v40
	v_exp_f32_e32 v41, v41
	v_mov_b32_dpp v42, v52 row_ror:1 row_mask:0xf bank_mask:0xf
	v_add_f32_e32 v40, 1.0, v40
	v_add_f32_e32 v41, 1.0, v41
	v_mov_b32_dpp v52, v38 row_shl:1 row_mask:0xf bank_mask:0xf bound_ctrl:1
	v_rcp_f32_e32 v40, v40
	v_rcp_f32_e32 v41, v41
	v_mov_b32_dpp v54, v34 row_shl:1 row_mask:0xf bank_mask:0xf bound_ctrl:1
	v_cndmask_b32_e64 v53, v39, v47, s[4:5]
	v_pk_add_f32 v[36:37], v[180:181], v[36:37]
	v_pk_mul_f32 v[32:33], v[32:33], v[40:41]
	v_mov_b32_dpp v47, v53 row_ror:1 row_mask:0xf bank_mask:0xf
	v_cndmask_b32_e64 v53, v35, v43, s[4:5]
	v_pk_mul_f32 v[34:35], v[34:35], v[236:237]
	v_pk_mul_f32 v[32:33], v[36:37], v[32:33]
	v_mov_b32_dpp v43, v53 row_ror:1 row_mask:0xf bank_mask:0xf
	v_pk_fma_f32 v[34:35], v[232:233], v[42:43], v[34:35]
	v_cvt_pk_bf16_f32 v32, v32, v33
	v_mov_b32_dpp v53, v39 row_shl:1 row_mask:0xf bank_mask:0xf bound_ctrl:1
	v_pk_mul_f32 v[38:39], v[38:39], v[248:249]
	v_cndmask_b32_e64 v40, v25, v17, s[6:7]
	v_mov_b32_dpp v55, v56 row_ror:15 row_mask:0xf bank_mask:0xf
	v_pk_fma_f32 v[34:35], v[240:241], v[54:55], v[34:35]
	v_pk_fma_f32 v[38:39], v[252:253], v[46:47], v[38:39]
	v_pk_add_f32 v[34:35], v[244:245], v[34:35]
	v_pk_fma_f32 v[38:39], v[192:193], v[52:53], v[38:39]
	v_mul_f32_e32 v36, 0xbfb8aa3b, v34
	v_exp_f32_e32 v36, v36
	v_mul_f32_e32 v37, 0xbfb8aa3b, v35
	v_exp_f32_e32 v37, v37
	v_pk_add_f32 v[38:39], v[182:183], v[38:39]
	v_add_f32_e32 v33, 1.0, v36
	v_rcp_f32_e32 v36, v33
	v_add_f32_e32 v33, 1.0, v37
	v_rcp_f32_e32 v37, v33
	s_nop 0
	v_pk_mul_f32 v[34:35], v[34:35], v[36:37]
	s_nop 0
	v_pk_mul_f32 v[34:35], v[38:39], v[34:35]
	s_nop 0
	v_cvt_pk_bf16_f32 v33, v34, v35
	global_store_dwordx2 v[96:97], v[32:33], off offset:32
	v_mov_b32_dpp v32, v28 row_shr:1 row_mask:0xf bank_mask:0xf bound_ctrl:1
	v_cndmask_b32_e64 v39, v29, v21, s[6:7]
	v_mov_b32_dpp v34, v24 row_shr:1 row_mask:0xf bank_mask:0xf bound_ctrl:1
	v_cndmask_b32_e64 v33, v28, v20, s[6:7]
	v_pk_fma_f32 v[52:53], v[28:29], v[246:247], v[180:181]
	s_nop 0
	v_mov_b32_dpp v36, v33 row_ror:15 row_mask:0xf bank_mask:0xf
	v_cndmask_b32_e64 v33, v24, v16, s[6:7]
	v_cndmask_b32_e64 v47, v31, v23, s[6:7]
	s_nop 0
	v_mov_b32_dpp v38, v33 row_ror:15 row_mask:0xf bank_mask:0xf
	v_cndmask_b32_e64 v50, v27, v19, s[6:7]
	s_nop 0
	v_mov_b32_dpp v33, v29 row_shr:1 row_mask:0xf bank_mask:0xf bound_ctrl:1
	v_pk_fma_f32 v[32:33], v[250:251], v[32:33], v[52:53]
	s_nop 0
	v_mov_b32_dpp v35, v25 row_shr:1 row_mask:0xf bank_mask:0xf bound_ctrl:1
	v_pk_fma_f32 v[34:35], v[230:231], v[34:35], v[48:49]
	s_nop 0
	v_mov_b32_dpp v37, v39 row_ror:15 row_mask:0xf bank_mask:0xf
	v_pk_fma_f32 v[32:33], v[190:191], v[36:37], v[32:33]
	s_nop 0
	v_mov_b32_dpp v39, v40 row_ror:15 row_mask:0xf bank_mask:0xf
	v_pk_fma_f32 v[34:35], v[238:239], v[38:39], v[34:35]
	s_nop 0
	v_mul_f32_e32 v38, 0xbfb8aa3b, v34
	v_mul_f32_e32 v49, 0xbfb8aa3b, v35
	v_exp_f32_e32 v48, v38
	v_exp_f32_e32 v49, v49
	v_mov_b32_dpp v40, v30 row_shr:1 row_mask:0xf bank_mask:0xf bound_ctrl:1
	v_add_f32_e32 v48, 1.0, v48
	v_add_f32_e32 v49, 1.0, v49
	v_mov_b32_dpp v42, v26 row_shr:1 row_mask:0xf bank_mask:0xf bound_ctrl:1
	v_cndmask_b32_e64 v41, v30, v22, s[6:7]
	v_rcp_f32_e32 v48, v48
	v_rcp_f32_e32 v49, v49
	v_mov_b32_dpp v44, v41 row_ror:15 row_mask:0xf bank_mask:0xf
	v_cndmask_b32_e64 v41, v26, v18, s[6:7]
	v_pk_fma_f32 v[38:39], v[26:27], v[236:237], v[244:245]
	v_pk_mul_f32 v[34:35], v[34:35], v[48:49]
	v_mov_b32_dpp v46, v41 row_ror:15 row_mask:0xf bank_mask:0xf
	v_pk_mul_f32 v[32:33], v[32:33], v[34:35]
	s_nop 0
	v_mov_b32_dpp v41, v31 row_shr:1 row_mask:0xf bank_mask:0xf bound_ctrl:1
	v_cvt_pk_bf16_f32 v32, v32, v33
	s_nop 0
	v_mov_b32_dpp v43, v27 row_shr:1 row_mask:0xf bank_mask:0xf bound_ctrl:1
	v_pk_fma_f32 v[34:35], v[232:233], v[42:43], v[38:39]
	v_cndmask_b32_e64 v42, v19, v11, s[6:7]
	v_mov_b32_dpp v45, v47 row_ror:15 row_mask:0xf bank_mask:0xf
	s_nop 1
	v_mov_b32_dpp v47, v50 row_ror:15 row_mask:0xf bank_mask:0xf
	v_pk_fma_f32 v[34:35], v[240:241], v[46:47], v[34:35]
	v_pk_fma_f32 v[50:51], v[30:31], v[248:249], v[182:183]
	s_nop 0
	v_pk_fma_f32 v[38:39], v[252:253], v[40:41], v[50:51]
	v_mul_f32_e32 v36, 0xbfb8aa3b, v34
	v_exp_f32_e32 v36, v36
	v_mul_f32_e32 v37, 0xbfb8aa3b, v35
	v_exp_f32_e32 v37, v37
	v_pk_fma_f32 v[38:39], v[192:193], v[44:45], v[38:39]
	v_add_f32_e32 v33, 1.0, v36
	v_rcp_f32_e32 v36, v33
	v_add_f32_e32 v33, 1.0, v37
	v_rcp_f32_e32 v37, v33
	v_pk_fma_f32 v[40:41], v[16:17], v[234:235], v[242:243]
	v_pk_fma_f32 v[44:45], v[20:21], v[246:247], v[180:181]
	v_pk_mul_f32 v[34:35], v[34:35], v[36:37]
	v_cndmask_b32_e64 v36, v17, v9, s[6:7]
	v_pk_mul_f32 v[34:35], v[38:39], v[34:35]
	v_cndmask_b32_e64 v37, v22, v14, s[6:7]
	v_cvt_pk_bf16_f32 v33, v34, v35
	global_store_dwordx2 v[98:99], v[32:33], off offset:32
	v_cndmask_b32_e64 v32, v20, v28, s[4:5]
	v_cndmask_b32_e64 v33, v20, v12, s[6:7]
	s_nop 0
	v_mov_b32_dpp v28, v32 row_ror:1 row_mask:0xf bank_mask:0xf
	v_cndmask_b32_e64 v32, v16, v24, s[4:5]
	v_cndmask_b32_e64 v35, v21, v13, s[6:7]
	s_nop 0
	v_mov_b32_dpp v24, v32 row_ror:1 row_mask:0xf bank_mask:0xf
	v_cndmask_b32_e64 v39, v23, v15, s[6:7]
; __device__ __forceinline__ void st_bf4(bf16_t* p, f32x4 v) { u32x2 w; w.x = pk2(v[0], v[1]); w.y = pk2(v[2], v[3]); *(u32x2*)p = w; }
; __device__ __forceinline__ float sigmoidf_(float x) { return __builtin_amdgcn_rcpf(1.f + __expf(-x)); }
; __device__ __forceinline__ float dpp_ror1(float v) { return __int_as_float(__builtin_amdgcn_update_dpp(0, __float_as_int(v), 0x121, 0xf, 0xf, false)); }
; __device__ __forceinline__ float dpp_rol1(float v) { return __int_as_float(__builtin_amdgcn_update_dpp(0, __float_as_int(v), 0x12F, 0xf, 0xf, false)); }
;     __device__ __forceinline__ void tile(const f32x4 (&acc)[2][2][4][2], const Unit& u, int wr, int wc, int fr, int fq) const {
;     ...
;         for (int n = 0; n < 2; ++n) {
;             const int cv = 128 * u.pn + 32 * wc + 16 * n + 4 * fq, cg = FF + cv;
;             const f32x4 wv0 = *(const f32x4*)(cw + cv), wv1 = *(const f32x4*)(cw + F2 + cv), wv2 = *(const f32x4*)(cw + 2 * F2 + cv), bv = *(const f32x4*)(cb + cv);
;             const f32x4 wg0 = *(const f32x4*)(cw + cg), wg1 = *(const f32x4*)(cw + F2 + cg), wg2 = *(const f32x4*)(cw + 2 * F2 + cg), bg = *(const f32x4*)(cb + cg);
; #pragma unroll
;             for (int ai = 0; ai < 2; ++ai)
; #pragma unroll
;                 for (int m = 0; m < 4; ++m) {
;                     f32x4 r;
; #pragma unroll
;                     for (int i = 0; i < 4; ++i) {
;                         const float xv = acc[ai][0][m][n][i], xg = acc[ai][1][m][n][i];
;                         const float uv = m > 0 ? acc[ai][0][m > 0 ? m - 1 : 0][n][i] : 0.f, ug = m > 0 ? acc[ai][1][m > 0 ? m - 1 : 0][n][i] : 0.f;
;                         const float dv = m < 3 ? acc[ai][0][m < 3 ? m + 1 : 3][n][i] : 0.f, dg = m < 3 ? acc[ai][1][m < 3 ? m + 1 : 3][n][i] : 0.f;
;                         const float pv = dpp_ror1(fr == 15 ? uv : xv), pg = dpp_ror1(fr == 15 ? ug : xg);
;                         const float nv = dpp_rol1(fr == 0 ? dv : xv), ng = dpp_rol1(fr == 0 ? dg : xg);
;                         const float yv = wv0[i] * pv + wv1[i] * xv + wv2[i] * nv + bv[i];
;                         const float yg = wg0[i] * pg + wg1[i] * xg + wg2[i] * ng + bg[i];
;                         r[i] = yg * sigmoidf_(yg) * yv;
;                     }
;                     st_bf4(ACT + (size_t)(u.pm * BM + ai * HALF + wr * 64 + m * 16 + fr) * FF + cv, r);
	s_nop 0
	v_mov_b32_dpp v32, v33 row_ror:15 row_mask:0xf bank_mask:0xf
	v_cndmask_b32_e64 v33, v16, v8, s[6:7]
	s_nop 1
	v_mov_b32_dpp v34, v33 row_ror:15 row_mask:0xf bank_mask:0xf
	v_cndmask_b32_e64 v33, v21, v29, s[4:5]
	s_nop 1
	v_mov_b32_dpp v29, v33 row_ror:1 row_mask:0xf bank_mask:0xf
	v_cndmask_b32_e64 v33, v17, v25, s[4:5]
	v_pk_fma_f32 v[28:29], v[250:251], v[28:29], v[44:45]
	s_nop 0
	v_mov_b32_dpp v25, v33 row_ror:1 row_mask:0xf bank_mask:0xf
	v_pk_fma_f32 v[24:25], v[230:231], v[24:25], v[40:41]
	s_nop 0
	v_mov_b32_dpp v33, v35 row_ror:15 row_mask:0xf bank_mask:0xf
	v_pk_fma_f32 v[28:29], v[190:191], v[32:33], v[28:29]
	v_pk_fma_f32 v[32:33], v[8:9], v[234:235], v[242:243]
	v_mov_b32_dpp v35, v36 row_ror:15 row_mask:0xf bank_mask:0xf
	v_pk_fma_f32 v[24:25], v[238:239], v[34:35], v[24:25]
	v_cndmask_b32_e64 v36, v22, v30, s[4:5]
	v_mul_f32_e32 v34, 0xbfb8aa3b, v24
	v_mul_f32_e32 v41, 0xbfb8aa3b, v25
	v_mov_b32_dpp v30, v36 row_ror:1 row_mask:0xf bank_mask:0xf
	v_cndmask_b32_e64 v36, v18, v26, s[4:5]
	v_exp_f32_e32 v40, v34
	v_exp_f32_e32 v41, v41
	v_mov_b32_dpp v26, v36 row_ror:1 row_mask:0xf bank_mask:0xf
	v_add_f32_e32 v40, 1.0, v40
	v_add_f32_e32 v41, 1.0, v41
	v_mov_b32_dpp v36, v37 row_ror:15 row_mask:0xf bank_mask:0xf
	v_cndmask_b32_e64 v37, v18, v10, s[6:7]
	v_rcp_f32_e32 v40, v40
	v_rcp_f32_e32 v41, v41
	v_mov_b32_dpp v38, v37 row_ror:15 row_mask:0xf bank_mask:0xf
	v_cndmask_b32_e64 v37, v23, v31, s[4:5]
	v_pk_mul_f32 v[34:35], v[18:19], v[236:237]
	s_nop 0
	v_mov_b32_dpp v31, v37 row_ror:1 row_mask:0xf bank_mask:0xf
	v_cndmask_b32_e64 v37, v19, v27, s[4:5]
	v_pk_mul_f32 v[24:25], v[24:25], v[40:41]
	s_nop 0
	v_mov_b32_dpp v27, v37 row_ror:1 row_mask:0xf bank_mask:0xf
	v_pk_fma_f32 v[26:27], v[232:233], v[26:27], v[34:35]
	v_pk_mul_f32 v[24:25], v[28:29], v[24:25]
	v_mov_b32_dpp v37, v39 row_ror:15 row_mask:0xf bank_mask:0xf
	v_cvt_pk_bf16_f32 v24, v24, v25
	v_cndmask_b32_e64 v34, v11, v3, s[6:7]
	v_mov_b32_dpp v39, v42 row_ror:15 row_mask:0xf bank_mask:0xf
	v_pk_fma_f32 v[26:27], v[240:241], v[38:39], v[26:27]
	v_pk_fma_f32 v[42:43], v[22:23], v[248:249], v[182:183]
	v_pk_add_f32 v[26:27], v[244:245], v[26:27]
	v_pk_fma_f32 v[30:31], v[252:253], v[30:31], v[42:43]
	v_mul_f32_e32 v28, 0xbfb8aa3b, v26
	v_exp_f32_e32 v28, v28
	v_mul_f32_e32 v29, 0xbfb8aa3b, v27
	v_exp_f32_e32 v29, v29
	v_pk_fma_f32 v[30:31], v[192:193], v[36:37], v[30:31]
	v_add_f32_e32 v25, 1.0, v28
	v_rcp_f32_e32 v28, v25
	v_add_f32_e32 v25, 1.0, v29
	v_rcp_f32_e32 v29, v25
	v_pk_fma_f32 v[36:37], v[12:13], v[246:247], v[180:181]
	v_pk_mul_f32 v[26:27], v[26:27], v[28:29]
	s_nop 0
	v_pk_mul_f32 v[26:27], v[30:31], v[26:27]
	v_cndmask_b32_e64 v28, v9, v1, s[6:7]
	v_cvt_pk_bf16_f32 v25, v26, v27
	global_store_dwordx2 v[100:101], v[24:25], off offset:32
	v_cndmask_b32_e64 v24, v12, v20, s[4:5]
	v_cndmask_b32_e64 v25, v12, v4, s[6:7]
	s_nop 0
	v_mov_b32_dpp v20, v24 row_ror:1 row_mask:0xf bank_mask:0xf
	v_cndmask_b32_e64 v24, v8, v16, s[4:5]
	v_cndmask_b32_e64 v27, v13, v5, s[6:7]
	v_cndmask_b32_e64 v29, v14, v6, s[6:7]
	v_mov_b32_dpp v16, v24 row_ror:1 row_mask:0xf bank_mask:0xf
	v_cndmask_b32_e64 v31, v15, v7, s[6:7]
	v_mov_b32_dpp v24, v25 row_ror:15 row_mask:0xf bank_mask:0xf
	v_cndmask_b32_e64 v25, v8, v0, s[6:7]
	s_nop 1
	v_mov_b32_dpp v26, v25 row_ror:15 row_mask:0xf bank_mask:0xf
	v_cndmask_b32_e64 v25, v13, v21, s[4:5]
	s_nop 1
	v_mov_b32_dpp v21, v25 row_ror:1 row_mask:0xf bank_mask:0xf
	v_cndmask_b32_e64 v25, v9, v17, s[4:5]
	v_pk_fma_f32 v[20:21], v[250:251], v[20:21], v[36:37]
	s_nop 0
	v_mov_b32_dpp v17, v25 row_ror:1 row_mask:0xf bank_mask:0xf
	v_pk_fma_f32 v[16:17], v[230:231], v[16:17], v[32:33]
	s_nop 0
	v_mov_b32_dpp v25, v27 row_ror:15 row_mask:0xf bank_mask:0xf
	v_pk_fma_f32 v[20:21], v[190:191], v[24:25], v[20:21]
	v_cndmask_b32_e64 v24, v3, 0, s[6:7]
	v_mov_b32_dpp v27, v28 row_ror:15 row_mask:0xf bank_mask:0xf
	v_pk_fma_f32 v[16:17], v[238:239], v[26:27], v[16:17]
	v_cndmask_b32_e64 v28, v14, v22, s[4:5]
	v_mul_f32_e32 v26, 0xbfb8aa3b, v16
	v_mul_f32_e32 v33, 0xbfb8aa3b, v17
	v_mov_b32_dpp v22, v28 row_ror:1 row_mask:0xf bank_mask:0xf
	v_cndmask_b32_e64 v28, v10, v18, s[4:5]
	v_exp_f32_e32 v32, v26
	v_exp_f32_e32 v33, v33
	v_mov_b32_dpp v18, v28 row_ror:1 row_mask:0xf bank_mask:0xf
	v_add_f32_e32 v32, 1.0, v32
	v_add_f32_e32 v33, 1.0, v33
	v_mov_b32_dpp v28, v29 row_ror:15 row_mask:0xf bank_mask:0xf
	v_cndmask_b32_e64 v29, v10, v2, s[6:7]
; __device__ __forceinline__ void st_bf4(bf16_t* p, f32x4 v) { u32x2 w; w.x = pk2(v[0], v[1]); w.y = pk2(v[2], v[3]); *(u32x2*)p = w; }
; __device__ __forceinline__ float sigmoidf_(float x) { return __builtin_amdgcn_rcpf(1.f + __expf(-x)); }
; __device__ __forceinline__ float dpp_ror1(float v) { return __int_as_float(__builtin_amdgcn_update_dpp(0, __float_as_int(v), 0x121, 0xf, 0xf, false)); }
; __device__ __forceinline__ float dpp_rol1(float v) { return __int_as_float(__builtin_amdgcn_update_dpp(0, __float_as_int(v), 0x12F, 0xf, 0xf, false)); }
;     __device__ __forceinline__ void tile(const f32x4 (&acc)[2][2][4][2], const Unit& u, int wr, int wc, int fr, int fq) const {
;     ...
;         for (int n = 0; n < 2; ++n) {
;             const int cv = 128 * u.pn + 32 * wc + 16 * n + 4 * fq, cg = FF + cv;
;             const f32x4 wv0 = *(const f32x4*)(cw + cv), wv1 = *(const f32x4*)(cw + F2 + cv), wv2 = *(const f32x4*)(cw + 2 * F2 + cv), bv = *(const f32x4*)(cb + cv);
;             const f32x4 wg0 = *(const f32x4*)(cw + cg), wg1 = *(const f32x4*)(cw + F2 + cg), wg2 = *(const f32x4*)(cw + 2 * F2 + cg), bg = *(const f32x4*)(cb + cg);
; #pragma unroll
;             for (int ai = 0; ai < 2; ++ai)
; #pragma unroll
;                 for (int m = 0; m < 4; ++m) {
;                     f32x4 r;
; #pragma unroll
;                     for (int i = 0; i < 4; ++i) {
;                         const float xv = acc[ai][0][m][n][i], xg = acc[ai][1][m][n][i];
;                         const float uv = m > 0 ? acc[ai][0][m > 0 ? m - 1 : 0][n][i] : 0.f, ug = m > 0 ? acc[ai][1][m > 0 ? m - 1 : 0][n][i] : 0.f;
;                         const float dv = m < 3 ? acc[ai][0][m < 3 ? m + 1 : 3][n][i] : 0.f, dg = m < 3 ? acc[ai][1][m < 3 ? m + 1 : 3][n][i] : 0.f;
;                         const float pv = dpp_ror1(fr == 15 ? uv : xv), pg = dpp_ror1(fr == 15 ? ug : xg);
;                         const float nv = dpp_rol1(fr == 0 ? dv : xv), ng = dpp_rol1(fr == 0 ? dg : xg);
;                         const float yv = wv0[i] * pv + wv1[i] * xv + wv2[i] * nv + bv[i];
;                         const float yg = wg0[i] * pg + wg1[i] * xg + wg2[i] * ng + bg[i];
;                         r[i] = yg * sigmoidf_(yg) * yv;
;                     }
;                     st_bf4(ACT + (size_t)(u.pm * BM + ai * HALF + wr * 64 + m * 16 + fr) * FF + cv, r);
	v_rcp_f32_e32 v32, v32
	v_rcp_f32_e32 v33, v33
	v_mov_b32_dpp v30, v29 row_ror:15 row_mask:0xf bank_mask:0xf
	v_cndmask_b32_e64 v29, v15, v23, s[4:5]
	v_pk_fma_f32 v[26:27], v[10:11], v[236:237], v[244:245]
	s_nop 0
	v_mov_b32_dpp v23, v29 row_ror:1 row_mask:0xf bank_mask:0xf
	v_cndmask_b32_e64 v29, v11, v19, s[4:5]
	v_pk_mul_f32 v[16:17], v[16:17], v[32:33]
	s_nop 0
	v_mov_b32_dpp v19, v29 row_ror:1 row_mask:0xf bank_mask:0xf
	v_pk_fma_f32 v[18:19], v[232:233], v[18:19], v[26:27]
	v_pk_mul_f32 v[16:17], v[20:21], v[16:17]
	v_mov_b32_dpp v29, v31 row_ror:15 row_mask:0xf bank_mask:0xf
	v_cvt_pk_bf16_f32 v16, v16, v17
	s_nop 0
	v_mov_b32_dpp v31, v34 row_ror:15 row_mask:0xf bank_mask:0xf
	v_pk_fma_f32 v[18:19], v[240:241], v[30:31], v[18:19]
	v_pk_fma_f32 v[34:35], v[14:15], v[248:249], v[182:183]
	s_nop 0
	v_pk_fma_f32 v[22:23], v[252:253], v[22:23], v[34:35]
	v_mul_f32_e32 v20, 0xbfb8aa3b, v18
	v_exp_f32_e32 v20, v20
	v_mul_f32_e32 v21, 0xbfb8aa3b, v19
	v_exp_f32_e32 v21, v21
	v_pk_fma_f32 v[22:23], v[192:193], v[28:29], v[22:23]
	v_add_f32_e32 v17, 1.0, v20
	v_rcp_f32_e32 v20, v17
	v_add_f32_e32 v17, 1.0, v21
	v_rcp_f32_e32 v21, v17
	s_nop 0
	v_pk_mul_f32 v[18:19], v[18:19], v[20:21]
	s_nop 0
	v_pk_mul_f32 v[18:19], v[22:23], v[18:19]
	v_cndmask_b32_e64 v20, v1, 0, s[6:7]
	v_cvt_pk_bf16_f32 v17, v18, v19
	global_store_dwordx2 v[102:103], v[16:17], off offset:32
	v_cndmask_b32_e64 v16, v4, v12, s[4:5]
	s_nop 1
	v_mov_b32_dpp v12, v16 row_ror:1 row_mask:0xf bank_mask:0xf
	v_cndmask_b32_e64 v16, v0, v8, s[4:5]
	v_cndmask_b32_e64 v19, v5, 0, s[6:7]
	s_nop 0
	v_mov_b32_dpp v8, v16 row_ror:1 row_mask:0xf bank_mask:0xf
	v_cndmask_b32_e64 v23, v7, 0, s[6:7]
	v_mov_b32_dpp v16, v4 row_shl:1 row_mask:0xf bank_mask:0xf bound_ctrl:1
	s_nop 1
	v_mov_b32_dpp v18, v0 row_shl:1 row_mask:0xf bank_mask:0xf bound_ctrl:1
	v_cndmask_b32_e64 v17, v5, v13, s[4:5]
	v_pk_mul_f32 v[4:5], v[4:5], v[246:247]
	s_nop 0
	v_mov_b32_dpp v13, v17 row_ror:1 row_mask:0xf bank_mask:0xf
	v_cndmask_b32_e64 v17, v1, v9, s[4:5]
	v_pk_mul_f32 v[0:1], v[0:1], v[234:235]
	v_pk_fma_f32 v[4:5], v[250:251], v[12:13], v[4:5]
	v_mov_b32_dpp v9, v17 row_ror:1 row_mask:0xf bank_mask:0xf
	v_pk_fma_f32 v[0:1], v[230:231], v[8:9], v[0:1]
	s_nop 0
	v_mov_b32_dpp v17, v19 row_ror:15 row_mask:0xf bank_mask:0xf
	v_pk_fma_f32 v[4:5], v[190:191], v[16:17], v[4:5]
	s_nop 0
	v_mov_b32_dpp v19, v20 row_ror:15 row_mask:0xf bank_mask:0xf
	v_pk_fma_f32 v[0:1], v[238:239], v[18:19], v[0:1]
	v_cndmask_b32_e64 v20, v6, v14, s[4:5]
	v_pk_add_f32 v[0:1], v[242:243], v[0:1]
	s_nop 0
	v_mul_f32_e32 v8, 0xbfb8aa3b, v1
	v_exp_f32_e32 v8, v8
	v_mul_f32_e32 v9, 0xbfb8aa3b, v0
	v_mov_b32_dpp v14, v20 row_ror:1 row_mask:0xf bank_mask:0xf
	v_cndmask_b32_e64 v20, v2, v10, s[4:5]
	v_exp_f32_e32 v18, v9
	v_add_f32_e32 v8, 1.0, v8
	v_mov_b32_dpp v10, v20 row_ror:1 row_mask:0xf bank_mask:0xf
	v_rcp_f32_e32 v9, v8
	v_add_f32_e32 v8, 1.0, v18
	v_mov_b32_dpp v20, v6 row_shl:1 row_mask:0xf bank_mask:0xf bound_ctrl:1
	v_rcp_f32_e32 v8, v8
	v_pk_add_f32 v[4:5], v[180:181], v[4:5]
	v_mov_b32_dpp v22, v2 row_shl:1 row_mask:0xf bank_mask:0xf bound_ctrl:1
	v_cndmask_b32_e64 v21, v7, v15, s[4:5]
	v_pk_mul_f32 v[0:1], v[0:1], v[8:9]
	v_pk_mul_f32 v[6:7], v[6:7], v[248:249]
	v_mov_b32_dpp v15, v21 row_ror:1 row_mask:0xf bank_mask:0xf
	v_cndmask_b32_e64 v21, v3, v11, s[4:5]
	v_pk_mul_f32 v[2:3], v[2:3], v[236:237]
	v_pk_mul_f32 v[0:1], v[4:5], v[0:1]
	v_mov_b32_dpp v11, v21 row_ror:1 row_mask:0xf bank_mask:0xf
	v_pk_fma_f32 v[2:3], v[232:233], v[10:11], v[2:3]
	v_cvt_pk_bf16_f32 v0, v0, v1
	v_mov_b32_dpp v21, v23 row_ror:15 row_mask:0xf bank_mask:0xf
	v_pk_fma_f32 v[6:7], v[252:253], v[14:15], v[6:7]
	s_nop 0
	v_mov_b32_dpp v23, v24 row_ror:15 row_mask:0xf bank_mask:0xf
	v_pk_fma_f32 v[2:3], v[240:241], v[22:23], v[2:3]
	v_pk_fma_f32 v[6:7], v[192:193], v[20:21], v[6:7]
	v_pk_add_f32 v[2:3], v[244:245], v[2:3]
	v_pk_add_f32 v[6:7], v[182:183], v[6:7]
	v_mul_f32_e32 v4, 0xbfb8aa3b, v2
	v_exp_f32_e32 v4, v4
	v_mul_f32_e32 v5, 0xbfb8aa3b, v3
	v_exp_f32_e32 v5, v5
	v_add_f32_e32 v1, 1.0, v4
	v_rcp_f32_e32 v4, v1
	v_add_f32_e32 v1, 1.0, v5
	v_rcp_f32_e32 v5, v1
	s_nop 0
	v_pk_mul_f32 v[2:3], v[2:3], v[4:5]
	s_nop 0
	v_pk_mul_f32 v[2:3], v[6:7], v[2:3]
	s_nop 0
	v_cvt_pk_bf16_f32 v1, v2, v3
	global_store_dwordx2 v[104:105], v[0:1], off offset:32
	s_cbranch_vccnz .LBB0_1795
	s_andn2_b64 vcc, exec, s[2:3]
	s_cbranch_vccnz .LBB0_1794
	s_barrier
	s_branch .LBB0_1794
